# LayerNorm loops (phases 11, 14): the six-hop xor butterflies use v_permlane32/16_swap + DPP (row_ror, row_shl/shr, quad_perm) instead of ds_bpermute round trips; identical pairing
# speedup vs baseline: 1.0003x; 1.0003x over previous
.Lp11_ln:
	v_and_b32_e32 v2, 60, v206
	v_lshl_add_u32 v18, s2, 5, v2
	s_movk_i32 s14, 0x4000
	v_cmp_gt_i32_e32 vcc, s14, v18
	s_and_saveexec_b64 s[14:15], vcc
	s_cbranch_execz .LBB0_1365
	v_mbcnt_lo_u32_b32 v3, -1, 0
	v_mbcnt_hi_u32_b32 v3, -1, v3
	v_and_b32_e32 v7, 64, v3
	v_add_u32_e32 v7, 64, v7
	v_xor_b32_e32 v8, 32, v3
	v_cmp_lt_i32_e32 vcc, v8, v7
	v_lshlrev_b32_e32 v2, 3, v1
	v_and_b32_e32 v2, 0x1f8, v2
	v_cndmask_b32_e32 v8, v3, v8, vcc
	v_lshlrev_b32_e32 v71, 2, v8
	v_xor_b32_e32 v8, 16, v3
	v_cmp_lt_i32_e32 vcc, v8, v7
	v_mov_b32_e32 v21, 0
	v_lshlrev_b32_e32 v20, 1, v2
	v_cndmask_b32_e32 v8, v3, v8, vcc
	v_lshlrev_b32_e32 v72, 2, v8
	v_xor_b32_e32 v8, 8, v3
	v_cmp_lt_i32_e32 vcc, v8, v7
	v_lshl_add_u64 v[4:5], s[66:67], 0, v[20:21]
	s_lshl_b32 s19, s70, 5
	v_cndmask_b32_e32 v8, v3, v8, vcc
	v_lshlrev_b32_e32 v73, 2, v8
	v_xor_b32_e32 v8, 4, v3
	v_cmp_lt_i32_e32 vcc, v8, v7
	v_lshlrev_b32_e32 v20, 2, v2
	s_waitcnt lgkmcnt(0)
	v_lshl_add_u64 v[24:25], s[4:5], 0, v[20:21]
	v_cndmask_b32_e32 v8, v3, v8, vcc
	v_lshlrev_b32_e32 v74, 2, v8
	v_xor_b32_e32 v8, 2, v3
	v_cmp_lt_i32_e32 vcc, v8, v7
	v_lshl_add_u64 v[26:27], s[6:7], 0, v[20:21]
	s_add_u32 s6, s66, 0x1a00000
	v_cndmask_b32_e32 v8, v3, v8, vcc
	v_lshlrev_b32_e32 v75, 2, v8
	v_xor_b32_e32 v8, 1, v3
	v_cmp_lt_i32_e32 vcc, v8, v7
	s_mov_b64 s[4:5], 0x9c00000
	s_mov_b64 s[16:17], 0x5c00000
	v_or_b32_e32 v6, 0x200, v2
	s_addc_u32 s7, s67, 0
	v_cndmask_b32_e32 v3, v3, v8, vcc
	v_lshl_add_u64 v[28:29], v[4:5], 0, s[4:5]
	s_mov_b64 s[4:5], 0x1c00000
	s_mov_b32 s22, 0x3727c5ac
	v_lshl_add_u64 v[22:23], v[4:5], 0, s[16:17]
	v_lshlrev_b32_e32 v76, 2, v3
	v_lshl_add_u64 v[30:31], v[4:5], 0, s[4:5]
	s_mov_b64 s[4:5], 0
	s_movk_i32 s20, 0x1fff
	s_movk_i32 s21, 0x6000
	v_mov_b64_e32 v[32:33], s[6:7]
	s_mov_b64 s[6:7], 0x4000
	s_mov_b64 s[16:17], 0x3000
	v_lshlrev_b32_e32 v20, 2, v2
	s_mov_b32 s18, 0x3a800000
	v_lshlrev_b32_e32 v34, 2, v6
	v_mov_b32_e32 v35, v21
	v_mov_b64_e32 v[36:37], s[22:23]
	s_mov_b32 s22, 0x800000
	s_movk_i32 s23, 0x3fff
	global_load_dwordx4 v[130:133], v[24:25], off
	global_load_dwordx4 v[134:137], v[24:25], off offset:16
	global_load_dwordx4 v[138:141], v[24:25], off offset:2048
	global_load_dwordx4 v[142:145], v[24:25], off offset:2064
	global_load_dwordx4 v[146:149], v[26:27], off
	global_load_dwordx4 v[150:153], v[26:27], off offset:16
	global_load_dwordx4 v[154:157], v[26:27], off offset:2048
	global_load_dwordx4 v[158:161], v[26:27], off offset:2064
	s_waitcnt vmcnt(0)
	s_mov_b32 s40, 0
	s_mov_b32 s41, -1
	s_mov_b32 s42, 0xffff0000
	s_mov_b32 s43, 0xffff0000
.LBB0_1364:
	v_ashrrev_i32_e32 v19, 31, v18
	v_lshlrev_b64 v[40:41], 11, v[18:19]
	v_lshl_add_u64 v[10:11], v[22:23], 0, v[40:41]
	global_load_dwordx4 v[2:5], v[10:11], off
	global_load_dwordx4 v[6:9], v[10:11], off offset:1024
	v_add_u32_e32 v10, 1, v18
	v_ashrrev_i32_e32 v11, 31, v10
	v_lshlrev_b64 v[56:57], 11, v[10:11]
	v_lshl_add_u64 v[38:39], v[22:23], 0, v[56:57]
	global_load_dwordx4 v[10:13], v[38:39], off
	global_load_dwordx4 v[14:17], v[38:39], off offset:1024
	v_cmp_lt_i32_e32 vcc, s20, v18
	v_lshl_add_u64 v[110:111], v[28:29], 0, v[40:41]
	v_lshl_add_u64 v[114:115], v[30:31], 0, v[40:41]
	s_waitcnt vmcnt(0)
	v_lshlrev_b32_e32 v38, 16, v5
	v_and_b32_e32 v39, 0xffff0000, v5
	v_lshlrev_b32_e32 v42, 16, v4
	v_and_b32_e32 v43, 0xffff0000, v4
	v_lshlrev_b32_e32 v4, 16, v3
	v_lshlrev_b32_e32 v58, 16, v10
	v_and_b32_e32 v5, 0xffff0000, v3
	v_lshlrev_b32_e32 v48, 16, v2
	v_and_b32_e32 v49, 0xffff0000, v2
	v_lshlrev_b32_e32 v2, 16, v9
	v_and_b32_e32 v3, 0xffff0000, v9
	v_lshlrev_b32_e32 v50, 16, v8
	v_and_b32_e32 v51, 0xffff0000, v8
	v_lshlrev_b32_e32 v8, 16, v7
	v_and_b32_e32 v9, 0xffff0000, v7
	v_lshlrev_b32_e32 v52, 16, v6
	v_and_b32_e32 v53, 0xffff0000, v6
	v_lshlrev_b32_e32 v6, 16, v13
	v_and_b32_e32 v7, 0xffff0000, v13
	v_lshlrev_b32_e32 v54, 16, v12
	v_and_b32_e32 v55, 0xffff0000, v12
	v_lshlrev_b32_e32 v12, 16, v11
	v_and_b32_e32 v13, 0xffff0000, v11
	v_and_b32_e32 v59, 0xffff0000, v10
	v_lshlrev_b32_e32 v10, 16, v17
	v_and_b32_e32 v11, 0xffff0000, v17
	v_lshlrev_b32_e32 v62, 16, v16
	v_and_b32_e32 v63, 0xffff0000, v16
	v_lshlrev_b32_e32 v16, 16, v15
	v_and_b32_e32 v17, 0xffff0000, v15
	v_add_f32_e32 v15, 0, v58
	v_add_f32_e32 v19, 0, v48
	v_add_f32_e32 v15, v15, v59
	v_lshlrev_b32_e32 v90, 16, v14
	v_and_b32_e32 v91, 0xffff0000, v14
	v_add_f32_e32 v14, v19, v49
	v_add_f32_e32 v15, v15, v12
	v_add_f32_e32 v14, v14, v4
	v_add_f32_e32 v15, v15, v13
	v_add_f32_e32 v14, v14, v5
	v_add_f32_e32 v15, v15, v54
	v_add_f32_e32 v14, v14, v42
	v_add_f32_e32 v15, v15, v55
	v_add_f32_e32 v14, v14, v43
	v_add_f32_e32 v15, v15, v6
	v_add_f32_e32 v14, v14, v38
	v_add_f32_e32 v15, v15, v7
	v_add_f32_e32 v14, v14, v39
	v_add_f32_e32 v15, v15, v90
	v_add_f32_e32 v14, v14, v52
	v_add_f32_e32 v15, v15, v91
	v_add_f32_e32 v14, v14, v53
	v_add_f32_e32 v15, v15, v16
	v_add_f32_e32 v14, v14, v8
	v_add_f32_e32 v15, v15, v17
	v_add_f32_e32 v14, v14, v9
	v_add_f32_e32 v15, v15, v62
	v_add_f32_e32 v14, v14, v50
	v_add_f32_e32 v15, v15, v63
	v_add_f32_e32 v14, v14, v51
	v_add_f32_e32 v15, v15, v10
	v_add_f32_e32 v14, v14, v2
	v_add_f32_e32 v15, v15, v11
	v_add_f32_e32 v14, v14, v3
	v_mov_b32_e32 v200, v15
	v_mov_b32_e32 v201, v15
	s_nop 1
	v_permlane32_swap_b32 v200, v201
	v_cndmask_b32_e64 v44, v201, v200, s[40:41]
	v_mov_b32_e32 v200, v14
	v_mov_b32_e32 v201, v14
	s_nop 1
	v_permlane32_swap_b32 v200, v201
	v_cndmask_b32_e64 v19, v201, v200, s[40:41]
	s_waitcnt lgkmcnt(1)
	v_add_f32_e32 v15, v15, v44
	s_waitcnt lgkmcnt(0)
	v_add_f32_e32 v14, v14, v19
	v_mov_b32_e32 v200, v15
	v_mov_b32_e32 v201, v15
	s_nop 1
	v_permlane16_swap_b32 v200, v201
	v_cndmask_b32_e64 v44, v201, v200, s[42:43]
	v_mov_b32_e32 v200, v14
	v_mov_b32_e32 v201, v14
	s_nop 1
	v_permlane16_swap_b32 v200, v201
	v_cndmask_b32_e64 v19, v201, v200, s[42:43]
	s_waitcnt lgkmcnt(1)
	v_add_f32_e32 v15, v15, v44
	s_waitcnt lgkmcnt(0)
	v_add_f32_e32 v14, v14, v19
	s_nop 1
	v_mov_b32_dpp v44, v15 row_ror:8 row_mask:0xf bank_mask:0xf
	s_nop 1
	v_mov_b32_dpp v19, v14 row_ror:8 row_mask:0xf bank_mask:0xf
	s_waitcnt lgkmcnt(1)
	v_add_f32_e32 v15, v15, v44
	s_waitcnt lgkmcnt(0)
	v_add_f32_e32 v14, v14, v19
	s_nop 1
	v_mov_b32_dpp v44, v15 row_shl:4 row_mask:0xf bank_mask:0x5
	v_mov_b32_dpp v44, v15 row_shr:4 row_mask:0xf bank_mask:0xa
	s_nop 1
	v_mov_b32_dpp v19, v14 row_shl:4 row_mask:0xf bank_mask:0x5
	v_mov_b32_dpp v19, v14 row_shr:4 row_mask:0xf bank_mask:0xa
	s_waitcnt lgkmcnt(1)
	v_add_f32_e32 v15, v15, v44
	v_mov_b32_e32 v44, v134
	v_mov_b32_e32 v45, v135
	v_mov_b32_e32 v46, v136
	v_mov_b32_e32 v47, v137
	v_mov_b32_e32 v78, v130
	v_mov_b32_e32 v79, v131
	v_mov_b32_e32 v80, v132
	v_mov_b32_e32 v81, v133
	v_mov_b32_e32 v82, v150
	v_mov_b32_e32 v83, v151
	v_mov_b32_e32 v84, v152
	v_mov_b32_e32 v85, v153
	v_mov_b32_e32 v86, v146
	v_mov_b32_e32 v87, v147
	v_mov_b32_e32 v88, v148
	v_mov_b32_e32 v89, v149
	s_waitcnt lgkmcnt(0)
	v_add_f32_e32 v14, v14, v19
	s_nop 1
	v_mov_b32_dpp v19, v14 quad_perm:[2,3,0,1] row_mask:0xf bank_mask:0xf
	s_nop 1
	v_mov_b32_dpp v60, v15 quad_perm:[2,3,0,1] row_mask:0xf bank_mask:0xf
	s_waitcnt lgkmcnt(1)
	v_add_f32_e32 v14, v14, v19
	s_nop 1
	v_mov_b32_dpp v19, v14 quad_perm:[1,0,3,2] row_mask:0xf bank_mask:0xf
	s_waitcnt lgkmcnt(1)
	v_add_f32_e32 v15, v15, v60
	s_nop 1
	v_mov_b32_dpp v60, v15 quad_perm:[1,0,3,2] row_mask:0xf bank_mask:0xf
	s_waitcnt lgkmcnt(1)
	v_add_f32_e32 v14, v14, v19
	v_mul_f32_e32 v14, 0x3a800000, v14
	s_waitcnt lgkmcnt(0)
	v_add_f32_e32 v15, v15, v60
	v_pk_add_f32 v[106:107], v[2:3], v[14:15] op_sel_hi:[1,0] neg_lo:[0,1] neg_hi:[0,1]
	v_mul_f32_e32 v2, 0x3a800000, v15
	v_pk_add_f32 v[92:93], v[48:49], v[14:15] op_sel_hi:[1,0] neg_lo:[0,1] neg_hi:[0,1]
	v_pk_add_f32 v[60:61], v[58:59], v[2:3] op_sel_hi:[1,0] neg_lo:[0,1] neg_hi:[0,1]
	v_pk_add_f32 v[98:99], v[38:39], v[14:15] op_sel_hi:[1,0] neg_lo:[0,1] neg_hi:[0,1]
	v_mov_b32_e32 v39, v93
	v_mov_b32_e32 v38, v61
	v_pk_add_f32 v[94:95], v[4:5], v[14:15] op_sel_hi:[1,0] neg_lo:[0,1] neg_hi:[0,1]
	v_pk_add_f32 v[96:97], v[42:43], v[14:15] op_sel_hi:[1,0] neg_lo:[0,1] neg_hi:[0,1]
	v_pk_add_f32 v[100:101], v[52:53], v[14:15] op_sel_hi:[1,0] neg_lo:[0,1] neg_hi:[0,1]
	v_pk_add_f32 v[102:103], v[8:9], v[14:15] op_sel_hi:[1,0] neg_lo:[0,1] neg_hi:[0,1]
	v_pk_add_f32 v[104:105], v[50:51], v[14:15] op_sel_hi:[1,0] neg_lo:[0,1] neg_hi:[0,1]
	v_mov_b32_e32 v15, v92
	v_pk_add_f32 v[64:65], v[12:13], v[2:3] op_sel_hi:[1,0] neg_lo:[0,1] neg_hi:[0,1]
	v_mov_b32_e32 v14, v60
	v_pk_mul_f32 v[38:39], v[38:39], v[38:39]
	v_mov_b32_e32 v13, v94
	v_mov_b32_e32 v12, v64
	v_pk_fma_f32 v[14:15], v[14:15], v[14:15], v[38:39]
	v_pk_add_f32 v[68:69], v[54:55], v[2:3] op_sel_hi:[1,0] neg_lo:[0,1] neg_hi:[0,1]
	v_pk_add_f32 v[66:67], v[6:7], v[2:3] op_sel_hi:[1,0] neg_lo:[0,1] neg_hi:[0,1]
	v_mov_b32_e32 v7, v95
	v_mov_b32_e32 v6, v65
	v_pk_fma_f32 v[12:13], v[12:13], v[12:13], v[14:15]
	v_pk_add_f32 v[50:51], v[16:17], v[2:3] op_sel_hi:[1,0] neg_lo:[0,1] neg_hi:[0,1]
	v_mov_b32_e32 v17, v96
	v_mov_b32_e32 v16, v68
	v_pk_fma_f32 v[6:7], v[6:7], v[6:7], v[12:13]
	v_mov_b32_e32 v43, v97
	v_mov_b32_e32 v42, v69
	v_pk_fma_f32 v[6:7], v[16:17], v[16:17], v[6:7]
	v_mov_b32_e32 v49, v98
	v_mov_b32_e32 v48, v66
	v_pk_fma_f32 v[6:7], v[42:43], v[42:43], v[6:7]
	v_pk_add_f32 v[52:53], v[90:91], v[2:3] op_sel_hi:[1,0] neg_lo:[0,1] neg_hi:[0,1]
	v_mov_b32_e32 v59, v99
	v_mov_b32_e32 v58, v67
	v_pk_fma_f32 v[6:7], v[48:49], v[48:49], v[6:7]
	v_mov_b32_e32 v90, v52
	v_pk_fma_f32 v[6:7], v[58:59], v[58:59], v[6:7]
	v_mov_b32_e32 v91, v100
	v_pk_fma_f32 v[6:7], v[90:91], v[90:91], v[6:7]
	v_mov_b32_e32 v12, v53
	v_mov_b32_e32 v13, v101
	v_pk_add_f32 v[54:55], v[62:63], v[2:3] op_sel_hi:[1,0] neg_lo:[0,1] neg_hi:[0,1]
	v_pk_fma_f32 v[6:7], v[12:13], v[12:13], v[6:7]
	v_mov_b32_e32 v12, v50
	v_mov_b32_e32 v13, v102
	v_pk_mul_f32 v[4:5], v[104:105], v[104:105]
	v_pk_mul_f32 v[62:63], v[54:55], v[54:55]
	v_pk_fma_f32 v[6:7], v[12:13], v[12:13], v[6:7]
	v_mov_b32_e32 v12, v51
	v_mov_b32_e32 v13, v103
	v_pk_fma_f32 v[6:7], v[12:13], v[12:13], v[6:7]
	v_mov_b32_e32 v12, v62
	v_mov_b32_e32 v13, v4
	v_pk_add_f32 v[58:59], v[10:11], v[2:3] op_sel_hi:[1,0] neg_lo:[0,1] neg_hi:[0,1]
	v_pk_mul_f32 v[8:9], v[106:107], v[106:107]
	v_pk_add_f32 v[6:7], v[12:13], v[6:7]
	v_pk_mul_f32 v[2:3], v[58:59], v[58:59]
	v_mov_b32_e32 v4, v63
	v_pk_add_f32 v[4:5], v[4:5], v[6:7]
	v_mov_b32_e32 v6, v2
	v_mov_b32_e32 v7, v8
	v_pk_add_f32 v[4:5], v[6:7], v[4:5]
	v_mov_b32_e32 v8, v3
	v_pk_add_f32 v[2:3], v[8:9], v[4:5]
	v_mov_b32_e32 v200, v3
	v_mov_b32_e32 v201, v3
	s_nop 1
	v_permlane32_swap_b32 v200, v201
	v_cndmask_b32_e64 v5, v201, v200, s[40:41]
	v_mov_b32_e32 v200, v2
	v_mov_b32_e32 v201, v2
	s_nop 1
	v_permlane32_swap_b32 v200, v201
	v_cndmask_b32_e64 v4, v201, v200, s[40:41]
	v_add_u32_e32 v6, 2, v18
	v_ashrrev_i32_e32 v7, 31, v6
	v_lshlrev_b64 v[48:49], 11, v[6:7]
	v_lshl_add_u64 v[6:7], v[22:23], 0, v[48:49]
	s_waitcnt lgkmcnt(0)
	v_pk_add_f32 v[2:3], v[2:3], v[4:5]
	v_mov_b32_e32 v200, v3
	v_mov_b32_e32 v201, v3
	s_nop 1
	v_permlane16_swap_b32 v200, v201
	v_cndmask_b32_e64 v5, v201, v200, s[42:43]
	v_mov_b32_e32 v200, v2
	v_mov_b32_e32 v201, v2
	s_nop 1
	v_permlane16_swap_b32 v200, v201
	v_cndmask_b32_e64 v4, v201, v200, s[42:43]
	global_load_dwordx4 v[14:17], v[6:7], off
	global_load_dwordx4 v[10:13], v[6:7], off offset:1024
	v_add_u32_e32 v6, 3, v18
	v_ashrrev_i32_e32 v7, 31, v6
	v_lshlrev_b64 v[38:39], 11, v[6:7]
	s_waitcnt lgkmcnt(0)
	v_pk_add_f32 v[2:3], v[2:3], v[4:5]
	s_nop 1
	v_mov_b32_dpp v5, v3 row_ror:8 row_mask:0xf bank_mask:0xf
	s_nop 1
	v_mov_b32_dpp v4, v2 row_ror:8 row_mask:0xf bank_mask:0xf
	v_lshl_add_u64 v[42:43], v[22:23], 0, v[38:39]
	v_add_u32_e32 v19, 0xffffe000, v18
	v_lshrrev_b32_e32 v19, 12, v19
	v_add_u32_e32 v19, 1, v19
	s_waitcnt lgkmcnt(0)
	v_pk_add_f32 v[2:3], v[2:3], v[4:5]
	s_nop 1
	v_mov_b32_dpp v5, v3 row_shl:4 row_mask:0xf bank_mask:0x5
	v_mov_b32_dpp v5, v3 row_shr:4 row_mask:0xf bank_mask:0xa
	s_nop 1
	v_mov_b32_dpp v4, v2 row_shl:4 row_mask:0xf bank_mask:0x5
	v_mov_b32_dpp v4, v2 row_shr:4 row_mask:0xf bank_mask:0xa
	v_cndmask_b32_e32 v19, 0, v19, vcc
	v_add_u32_e32 v18, s19, v18
	s_waitcnt lgkmcnt(0)
	v_pk_add_f32 v[62:63], v[2:3], v[4:5]
	s_nop 1
	v_mov_b32_dpp v91, v63 quad_perm:[2,3,0,1] row_mask:0xf bank_mask:0xf
	s_nop 1
	v_mov_b32_dpp v90, v62 quad_perm:[2,3,0,1] row_mask:0xf bank_mask:0xf
	global_load_dwordx4 v[6:9], v[42:43], off
	global_load_dwordx4 v[2:5], v[42:43], off offset:1024
	s_waitcnt lgkmcnt(0)
	v_pk_add_f32 v[42:43], v[62:63], v[90:91]
	s_nop 1
	v_mov_b32_dpp v63, v43 quad_perm:[1,0,3,2] row_mask:0xf bank_mask:0xf
	s_nop 1
	v_mov_b32_dpp v62, v42 quad_perm:[1,0,3,2] row_mask:0xf bank_mask:0xf
	v_mad_u64_u32 v[90:91], s[24:25], v19, s21, v[32:33]
	v_lshl_add_u64 v[108:109], v[90:91], 0, s[6:7]
	s_waitcnt lgkmcnt(0)
	v_pk_add_f32 v[42:43], v[42:43], v[62:63]
	s_nop 0
	v_pk_fma_f32 v[62:63], v[42:43], s[18:19], v[36:37] op_sel_hi:[1,0,0]
	v_lshl_add_u64 v[42:43], v[108:109], 0, v[20:21]
	v_mul_f32_e32 v19, 0x4b800000, v63
	v_cmp_gt_f32_e32 vcc, s22, v63
	s_nop 1
	v_cndmask_b32_e32 v19, v63, v19, vcc
	v_rsq_f32_e32 v19, v19
	s_nop 0
	v_mul_f32_e32 v63, 0x45800000, v19
	v_cndmask_b32_e32 v70, v19, v63, vcc
	v_pk_mul_f32 v[92:93], v[92:93], v[70:71] op_sel_hi:[1,0]
	v_mul_f32_e32 v19, 0x4b800000, v62
	s_waitcnt vmcnt(4)
	v_pk_fma_f32 v[112:113], v[78:79], v[92:93], v[86:87]
	v_pk_mul_f32 v[78:79], v[96:97], v[70:71] op_sel_hi:[1,0]
	v_cmp_gt_f32_e32 vcc, s22, v62
	v_pk_fma_f32 v[96:97], v[44:45], v[78:79], v[82:83]
	v_pk_mul_f32 v[44:45], v[94:95], v[70:71] op_sel_hi:[1,0]
	v_cndmask_b32_e32 v19, v62, v19, vcc
	v_pk_fma_f32 v[94:95], v[80:81], v[44:45], v[88:89]
	v_pk_mul_f32 v[44:45], v[98:99], v[70:71] op_sel_hi:[1,0]
	v_rsq_f32_e32 v19, v19
	v_pk_fma_f32 v[98:99], v[46:47], v[44:45], v[84:85]
	v_cvt_pk_bf16_f32 v44, v112, v113
	v_cvt_pk_bf16_f32 v45, v94, v95
	v_cvt_pk_bf16_f32 v46, v96, v97
	v_cvt_pk_bf16_f32 v47, v98, v99
	global_store_dwordx4 v[110:111], v[44:47], off
	global_load_dwordx4 v[78:81], v[42:43], off
	global_load_dwordx4 v[82:85], v[42:43], off offset:16
	v_lshl_add_u64 v[46:47], v[90:91], 0, s[16:17]
	v_lshl_add_u64 v[44:45], v[46:47], 0, v[20:21]
	global_load_dwordx4 v[86:89], v[44:45], off
	global_load_dwordx4 v[90:93], v[44:45], off offset:16
	v_lshl_add_u64 v[46:47], v[46:47], 0, v[34:35]
	v_lshl_add_u64 v[62:63], v[28:29], 0, v[56:57]
	v_lshl_add_u64 v[56:57], v[30:31], 0, v[56:57]
	s_waitcnt vmcnt(3)
	v_pk_add_f32 v[40:41], v[78:79], 1.0 op_sel_hi:[1,0]
	s_waitcnt vmcnt(2)
	v_pk_add_f32 v[78:79], v[82:83], 1.0 op_sel_hi:[1,0]
	v_pk_add_f32 v[80:81], v[80:81], 1.0 op_sel_hi:[1,0]
	v_pk_add_f32 v[82:83], v[84:85], 1.0 op_sel_hi:[1,0]
	s_waitcnt vmcnt(1)
	v_pk_fma_f32 v[40:41], v[40:41], v[112:113], v[86:87]
	s_waitcnt vmcnt(0)
	v_pk_fma_f32 v[84:85], v[78:79], v[96:97], v[90:91]
	v_pk_fma_f32 v[80:81], v[80:81], v[94:95], v[88:89]
	v_pk_fma_f32 v[82:83], v[82:83], v[98:99], v[92:93]
	v_cvt_pk_bf16_f32 v78, v40, v41
	v_cvt_pk_bf16_f32 v79, v80, v81
	v_cvt_pk_bf16_f32 v80, v84, v85
	v_cvt_pk_bf16_f32 v81, v82, v83
	global_store_dwordx4 v[114:115], v[78:81], off
	s_nop 1
	v_mov_b32_e32 v78, v142
	v_mov_b32_e32 v79, v143
	v_mov_b32_e32 v80, v144
	v_mov_b32_e32 v81, v145
	s_nop 0
	v_mov_b32_e32 v82, v138
	v_mov_b32_e32 v83, v139
	v_mov_b32_e32 v84, v140
	v_mov_b32_e32 v85, v141
	v_mov_b32_e32 v86, v154
	v_mov_b32_e32 v87, v155
	v_mov_b32_e32 v88, v156
	v_mov_b32_e32 v89, v157
	v_mov_b32_e32 v90, v158
	v_mov_b32_e32 v91, v159
	v_mov_b32_e32 v92, v160
	v_mov_b32_e32 v93, v161
	v_pk_mul_f32 v[94:95], v[100:101], v[70:71] op_sel_hi:[1,0]
	v_pk_mul_f32 v[96:97], v[104:105], v[70:71] op_sel_hi:[1,0]
	v_pk_mul_f32 v[98:99], v[102:103], v[70:71] op_sel_hi:[1,0]
	v_pk_mul_f32 v[100:101], v[106:107], v[70:71] op_sel_hi:[1,0]
	v_lshl_add_u64 v[40:41], v[108:109], 0, v[34:35]
	v_mul_f32_e32 v70, 0x45800000, v19
	v_cndmask_b32_e32 v70, v19, v70, vcc
	v_pk_mul_f32 v[60:61], v[60:61], v[70:71] op_sel_hi:[1,0]
	v_pk_mul_f32 v[68:69], v[68:69], v[70:71] op_sel_hi:[1,0]
	v_pk_mul_f32 v[64:65], v[64:65], v[70:71] op_sel_hi:[1,0]
	v_pk_mul_f32 v[66:67], v[66:67], v[70:71] op_sel_hi:[1,0]
	v_lshlrev_b32_e32 v106, 16, v3
	v_and_b32_e32 v107, 0xffff0000, v3
	v_lshlrev_b32_e32 v108, 16, v2
	v_and_b32_e32 v109, 0xffff0000, v2
	v_lshlrev_b32_e32 v102, 16, v8
	v_and_b32_e32 v103, 0xffff0000, v8
	v_lshlrev_b32_e32 v8, 16, v7
	v_lshlrev_b32_e32 v104, 16, v5
	v_and_b32_e32 v105, 0xffff0000, v5
	v_pk_mul_f32 v[50:51], v[50:51], v[70:71] op_sel_hi:[1,0]
	s_waitcnt vmcnt(1)
	v_pk_fma_f32 v[94:95], v[82:83], v[94:95], v[86:87]
	s_waitcnt vmcnt(1)
	v_pk_fma_f32 v[96:97], v[78:79], v[96:97], v[90:91]
	v_pk_fma_f32 v[98:99], v[84:85], v[98:99], v[88:89]
	v_pk_fma_f32 v[100:101], v[80:81], v[100:101], v[92:93]
	v_cvt_pk_bf16_f32 v78, v94, v95
	v_cvt_pk_bf16_f32 v79, v98, v99
	v_cvt_pk_bf16_f32 v80, v96, v97
	v_cvt_pk_bf16_f32 v81, v100, v101
	global_store_dwordx4 v[110:111], v[78:81], off offset:1024
	global_load_dwordx4 v[78:81], v[40:41], off
	s_nop 0
	global_load_dwordx4 v[82:85], v[40:41], off offset:16
	global_load_dwordx4 v[86:89], v[46:47], off
	global_load_dwordx4 v[90:93], v[46:47], off offset:16
	s_waitcnt vmcnt(3)
	v_pk_add_f32 v[78:79], v[78:79], 1.0 op_sel_hi:[1,0]
	s_waitcnt vmcnt(2)
	v_pk_add_f32 v[82:83], v[82:83], 1.0 op_sel_hi:[1,0]
	v_pk_add_f32 v[80:81], v[80:81], 1.0 op_sel_hi:[1,0]
	v_pk_add_f32 v[84:85], v[84:85], 1.0 op_sel_hi:[1,0]
	s_waitcnt vmcnt(1)
	v_pk_fma_f32 v[78:79], v[78:79], v[94:95], v[86:87]
	s_waitcnt vmcnt(0)
	v_pk_fma_f32 v[82:83], v[82:83], v[96:97], v[90:91]
	v_pk_fma_f32 v[80:81], v[80:81], v[98:99], v[88:89]
	v_pk_fma_f32 v[84:85], v[84:85], v[100:101], v[92:93]
	v_cvt_pk_bf16_f32 v78, v78, v79
	v_cvt_pk_bf16_f32 v79, v80, v81
	v_cvt_pk_bf16_f32 v80, v82, v83
	v_cvt_pk_bf16_f32 v81, v84, v85
	global_store_dwordx4 v[114:115], v[78:81], off offset:1024
	s_nop 1
	v_mov_b32_e32 v78, v134
	v_mov_b32_e32 v79, v135
	v_mov_b32_e32 v80, v136
	v_mov_b32_e32 v81, v137
	s_nop 0
	v_mov_b32_e32 v82, v130
	v_mov_b32_e32 v83, v131
	v_mov_b32_e32 v84, v132
	v_mov_b32_e32 v85, v133
	v_mov_b32_e32 v86, v146
	v_mov_b32_e32 v87, v147
	v_mov_b32_e32 v88, v148
	v_mov_b32_e32 v89, v149
	v_mov_b32_e32 v90, v150
	v_mov_b32_e32 v91, v151
	v_mov_b32_e32 v92, v152
	v_mov_b32_e32 v93, v153
	v_lshlrev_b32_e32 v94, 16, v14
	v_lshlrev_b32_e32 v98, 16, v10
	v_and_b32_e32 v99, 0xffff0000, v10
	v_lshlrev_b32_e32 v10, 16, v6
	v_and_b32_e32 v95, 0xffff0000, v14
	v_lshlrev_b32_e32 v14, 16, v13
	v_lshlrev_b32_e32 v96, 16, v12
	v_and_b32_e32 v97, 0xffff0000, v12
	v_lshlrev_b32_e32 v12, 16, v11
	v_add_f32_e32 v2, 0, v94
	v_add_f32_e32 v3, 0, v10
	v_add_f32_e32 v2, v2, v95
	v_lshlrev_b32_e32 v100, 16, v9
	v_and_b32_e32 v101, 0xffff0000, v9
	v_and_b32_e32 v9, 0xffff0000, v7
	v_and_b32_e32 v7, 0xffff0000, v4
	s_waitcnt vmcnt(1)
	v_pk_fma_f32 v[60:61], v[82:83], v[60:61], v[86:87]
	s_waitcnt vmcnt(1)
	v_pk_fma_f32 v[68:69], v[78:79], v[68:69], v[90:91]
	v_pk_fma_f32 v[90:91], v[84:85], v[64:65], v[88:89]
	v_pk_fma_f32 v[92:93], v[80:81], v[66:67], v[92:93]
	v_cvt_pk_bf16_f32 v64, v60, v61
	v_cvt_pk_bf16_f32 v65, v90, v91
	v_cvt_pk_bf16_f32 v66, v68, v69
	v_cvt_pk_bf16_f32 v67, v92, v93
	global_store_dwordx4 v[62:63], v[64:67], off
	global_load_dwordx4 v[64:67], v[42:43], off
	s_nop 0
	global_load_dwordx4 v[78:81], v[42:43], off offset:16
	global_load_dwordx4 v[82:85], v[44:45], off
	global_load_dwordx4 v[86:89], v[44:45], off offset:16
	s_waitcnt vmcnt(3)
	v_pk_add_f32 v[64:65], v[64:65], 1.0 op_sel_hi:[1,0]
	s_waitcnt vmcnt(2)
	v_pk_add_f32 v[78:79], v[78:79], 1.0 op_sel_hi:[1,0]
	v_pk_add_f32 v[66:67], v[66:67], 1.0 op_sel_hi:[1,0]
	v_pk_add_f32 v[80:81], v[80:81], 1.0 op_sel_hi:[1,0]
	s_waitcnt vmcnt(1)
	v_pk_fma_f32 v[60:61], v[64:65], v[60:61], v[82:83]
	s_waitcnt vmcnt(0)
	v_pk_fma_f32 v[68:69], v[78:79], v[68:69], v[86:87]
	v_pk_fma_f32 v[66:67], v[66:67], v[90:91], v[84:85]
	v_pk_fma_f32 v[78:79], v[80:81], v[92:93], v[88:89]
	v_cvt_pk_bf16_f32 v64, v60, v61
	v_cvt_pk_bf16_f32 v65, v66, v67
	v_cvt_pk_bf16_f32 v66, v68, v69
	v_cvt_pk_bf16_f32 v67, v78, v79
	global_store_dwordx4 v[56:57], v[64:67], off
	s_nop 1
	v_mov_b32_e32 v64, v142
	v_mov_b32_e32 v65, v143
	v_mov_b32_e32 v66, v144
	v_mov_b32_e32 v67, v145
	s_nop 0
	v_mov_b32_e32 v78, v138
	v_mov_b32_e32 v79, v139
	v_mov_b32_e32 v80, v140
	v_mov_b32_e32 v81, v141
	v_mov_b32_e32 v82, v154
	v_mov_b32_e32 v83, v155
	v_mov_b32_e32 v84, v156
	v_mov_b32_e32 v85, v157
	v_mov_b32_e32 v86, v158
	v_mov_b32_e32 v87, v159
	v_mov_b32_e32 v88, v160
	v_mov_b32_e32 v89, v161
	v_lshlrev_b32_e32 v90, 16, v17
	v_and_b32_e32 v91, 0xffff0000, v17
	v_lshlrev_b32_e32 v92, 16, v16
	v_and_b32_e32 v93, 0xffff0000, v16
	v_lshlrev_b32_e32 v16, 16, v15
	v_and_b32_e32 v17, 0xffff0000, v15
	v_and_b32_e32 v15, 0xffff0000, v13
	v_and_b32_e32 v13, 0xffff0000, v11
	v_and_b32_e32 v11, 0xffff0000, v6
	v_add_f32_e32 v3, v3, v11
	v_add_f32_e32 v2, v2, v16
	v_add_f32_e32 v3, v3, v8
	v_add_f32_e32 v2, v2, v17
	v_add_f32_e32 v3, v3, v9
	v_add_f32_e32 v2, v2, v92
	v_add_f32_e32 v3, v3, v102
	v_add_f32_e32 v2, v2, v93
	v_add_f32_e32 v3, v3, v103
	v_add_f32_e32 v2, v2, v90
	v_add_f32_e32 v3, v3, v100
	v_add_f32_e32 v2, v2, v91
	v_add_f32_e32 v3, v3, v101
	v_add_f32_e32 v2, v2, v98
	v_add_f32_e32 v3, v3, v108
	v_add_f32_e32 v2, v2, v99
	v_add_f32_e32 v3, v3, v109
	v_add_f32_e32 v2, v2, v12
	v_add_f32_e32 v3, v3, v106
	v_lshlrev_b32_e32 v6, 16, v4
	v_add_f32_e32 v2, v2, v13
	v_add_f32_e32 v3, v3, v107
	v_add_f32_e32 v2, v2, v96
	v_add_f32_e32 v3, v3, v6
	v_add_f32_e32 v2, v2, v97
	v_add_f32_e32 v3, v3, v7
	v_add_f32_e32 v2, v2, v14
	v_add_f32_e32 v3, v3, v104
	v_add_f32_e32 v2, v2, v15
	v_add_f32_e32 v3, v3, v105
	v_mov_b32_e32 v200, v2
	v_mov_b32_e32 v201, v2
	s_nop 1
	v_permlane32_swap_b32 v200, v201
	v_cndmask_b32_e64 v4, v201, v200, s[40:41]
	v_mov_b32_e32 v200, v3
	v_mov_b32_e32 v201, v3
	s_nop 1
	v_permlane32_swap_b32 v200, v201
	v_cndmask_b32_e64 v5, v201, v200, s[40:41]
	s_waitcnt lgkmcnt(1)
	v_add_f32_e32 v19, v2, v4
	s_waitcnt lgkmcnt(0)
	v_add_f32_e32 v77, v3, v5
	v_pk_mul_f32 v[2:3], v[52:53], v[70:71] op_sel_hi:[1,0]
	v_pk_mul_f32 v[4:5], v[54:55], v[70:71] op_sel_hi:[1,0]
	v_pk_mul_f32 v[52:53], v[58:59], v[70:71] op_sel_hi:[1,0]
	v_mov_b32_e32 v200, v19
	v_mov_b32_e32 v201, v19
	s_nop 1
	v_permlane16_swap_b32 v200, v201
	v_cndmask_b32_e64 v110, v201, v200, s[42:43]
	s_waitcnt vmcnt(1)
	v_pk_fma_f32 v[54:55], v[78:79], v[2:3], v[82:83]
	s_waitcnt vmcnt(1)
	v_pk_fma_f32 v[78:79], v[64:65], v[4:5], v[86:87]
	v_pk_fma_f32 v[80:81], v[80:81], v[50:51], v[84:85]
	v_pk_fma_f32 v[82:83], v[66:67], v[52:53], v[88:89]
	v_cvt_pk_bf16_f32 v2, v54, v55
	v_cvt_pk_bf16_f32 v3, v80, v81
	v_cvt_pk_bf16_f32 v4, v78, v79
	v_cvt_pk_bf16_f32 v5, v82, v83
	global_store_dwordx4 v[62:63], v[2:5], off offset:1024
	global_load_dwordx4 v[50:53], v[40:41], off offset:16
	global_load_dwordx4 v[58:61], v[40:41], off
	s_nop 0
	global_load_dwordx4 v[62:65], v[46:47], off offset:16
	global_load_dwordx4 v[66:69], v[46:47], off
	v_mov_b32_e32 v200, v77
	v_mov_b32_e32 v201, v77
	s_nop 1
	v_permlane16_swap_b32 v200, v201
	v_cndmask_b32_e64 v2, v201, v200, s[42:43]
	s_waitcnt lgkmcnt(1)
	v_add_f32_e32 v3, v19, v110
	s_nop 1
	v_mov_b32_dpp v4, v3 row_ror:8 row_mask:0xf bank_mask:0xf
	s_waitcnt lgkmcnt(1)
	v_add_f32_e32 v2, v77, v2
	s_nop 1
	v_mov_b32_dpp v5, v2 row_ror:8 row_mask:0xf bank_mask:0xf
	s_waitcnt lgkmcnt(1)
	v_add_f32_e32 v3, v3, v4
	s_nop 1
	v_mov_b32_dpp v4, v3 row_shl:4 row_mask:0xf bank_mask:0x5
	v_mov_b32_dpp v4, v3 row_shr:4 row_mask:0xf bank_mask:0xa
	s_waitcnt lgkmcnt(1)
	v_add_f32_e32 v2, v2, v5
	s_nop 1
	v_mov_b32_dpp v5, v2 row_shl:4 row_mask:0xf bank_mask:0x5
	v_mov_b32_dpp v5, v2 row_shr:4 row_mask:0xf bank_mask:0xa
	s_waitcnt lgkmcnt(1)
	v_add_f32_e32 v3, v3, v4
	s_nop 1
	v_mov_b32_dpp v4, v3 quad_perm:[2,3,0,1] row_mask:0xf bank_mask:0xf
	s_waitcnt lgkmcnt(1)
	v_add_f32_e32 v2, v2, v5
	s_nop 1
	v_mov_b32_dpp v5, v2 quad_perm:[2,3,0,1] row_mask:0xf bank_mask:0xf
	s_waitcnt lgkmcnt(1)
	v_add_f32_e32 v3, v3, v4
	s_nop 1
	v_mov_b32_dpp v4, v3 quad_perm:[1,0,3,2] row_mask:0xf bank_mask:0xf
	s_waitcnt lgkmcnt(1)
	v_add_f32_e32 v2, v2, v5
	s_nop 1
	v_mov_b32_dpp v5, v2 quad_perm:[1,0,3,2] row_mask:0xf bank_mask:0xf
	s_waitcnt lgkmcnt(1)
	v_add_f32_e32 v3, v3, v4
	s_waitcnt lgkmcnt(0)
	v_add_f32_e32 v4, v2, v5
	v_mul_f32_e32 v2, 0x3a800000, v3
	v_mul_f32_e32 v70, 0x3a800000, v4
	v_pk_add_f32 v[84:85], v[94:95], v[2:3] op_sel_hi:[1,0] neg_lo:[0,1] neg_hi:[0,1]
	v_pk_add_f32 v[10:11], v[10:11], v[70:71] op_sel_hi:[1,0] neg_lo:[0,1] neg_hi:[0,1]
	v_pk_add_f32 v[86:87], v[16:17], v[2:3] op_sel_hi:[1,0] neg_lo:[0,1] neg_hi:[0,1]
	v_pk_add_f32 v[88:89], v[92:93], v[2:3] op_sel_hi:[1,0] neg_lo:[0,1] neg_hi:[0,1]
	v_pk_add_f32 v[90:91], v[90:91], v[2:3] op_sel_hi:[1,0] neg_lo:[0,1] neg_hi:[0,1]
	v_pk_add_f32 v[92:93], v[98:99], v[2:3] op_sel_hi:[1,0] neg_lo:[0,1] neg_hi:[0,1]
	v_pk_add_f32 v[94:95], v[12:13], v[2:3] op_sel_hi:[1,0] neg_lo:[0,1] neg_hi:[0,1]
	v_pk_add_f32 v[96:97], v[96:97], v[2:3] op_sel_hi:[1,0] neg_lo:[0,1] neg_hi:[0,1]
	v_pk_add_f32 v[98:99], v[14:15], v[2:3] op_sel_hi:[1,0] neg_lo:[0,1] neg_hi:[0,1]
	v_pk_add_f32 v[12:13], v[8:9], v[70:71] op_sel_hi:[1,0] neg_lo:[0,1] neg_hi:[0,1]
	v_pk_add_f32 v[2:3], v[106:107], v[70:71] op_sel_hi:[1,0] neg_lo:[0,1] neg_hi:[0,1]
	v_pk_add_f32 v[8:9], v[104:105], v[70:71] op_sel_hi:[1,0] neg_lo:[0,1] neg_hi:[0,1]
	v_mov_b32_e32 v106, v11
	v_mov_b32_e32 v107, v85
	v_pk_add_f32 v[16:17], v[102:103], v[70:71] op_sel_hi:[1,0] neg_lo:[0,1] neg_hi:[0,1]
	v_pk_mul_f32 v[102:103], v[98:99], v[98:99]
	v_mov_b32_e32 v104, v10
	v_mov_b32_e32 v105, v84
	v_pk_add_f32 v[4:5], v[108:109], v[70:71] op_sel_hi:[1,0] neg_lo:[0,1] neg_hi:[0,1]
	v_mov_b32_e32 v108, v12
	v_mov_b32_e32 v109, v86
	v_mov_b32_e32 v112, v13
	v_mov_b32_e32 v113, v87
	v_mov_b32_e32 v114, v16
	v_mov_b32_e32 v115, v88
	v_pk_add_f32 v[14:15], v[100:101], v[70:71] op_sel_hi:[1,0] neg_lo:[0,1] neg_hi:[0,1]
	v_mov_b32_e32 v116, v17
	v_mov_b32_e32 v117, v89
	v_mov_b32_e32 v118, v14
	v_mov_b32_e32 v119, v90
	v_mov_b32_e32 v120, v15
	v_mov_b32_e32 v121, v91
	v_mov_b32_e32 v122, v4
	v_mov_b32_e32 v123, v92
	v_mov_b32_e32 v124, v5
	v_mov_b32_e32 v125, v93
	v_pk_add_f32 v[6:7], v[6:7], v[70:71] op_sel_hi:[1,0] neg_lo:[0,1] neg_hi:[0,1]
	v_mov_b32_e32 v126, v2
	v_mov_b32_e32 v127, v94
	v_pk_mul_f32 v[100:101], v[96:97], v[96:97]
	v_pk_mul_f32 v[110:111], v[6:7], v[6:7]
	v_mov_b32_e32 v128, v3
	v_mov_b32_e32 v129, v95
	s_waitcnt vmcnt(3)
	v_pk_add_f32 v[50:51], v[50:51], 1.0 op_sel_hi:[1,0]
	s_waitcnt vmcnt(2)
	v_pk_add_f32 v[58:59], v[58:59], 1.0 op_sel_hi:[1,0]
	v_pk_add_f32 v[60:61], v[60:61], 1.0 op_sel_hi:[1,0]
	v_pk_add_f32 v[52:53], v[52:53], 1.0 op_sel_hi:[1,0]
	s_waitcnt vmcnt(0)
	v_pk_fma_f32 v[54:55], v[58:59], v[54:55], v[66:67]
	v_pk_fma_f32 v[58:59], v[50:51], v[78:79], v[62:63]
	v_pk_fma_f32 v[60:61], v[60:61], v[80:81], v[68:69]
	v_pk_fma_f32 v[62:63], v[52:53], v[82:83], v[64:65]
	v_cvt_pk_bf16_f32 v50, v54, v55
	v_cvt_pk_bf16_f32 v51, v60, v61
	v_cvt_pk_bf16_f32 v52, v58, v59
	v_cvt_pk_bf16_f32 v53, v62, v63
	global_store_dwordx4 v[56:57], v[50:53], off offset:1024
	s_nop 1
	v_mov_b32_e32 v50, v134
	v_mov_b32_e32 v51, v135
	v_mov_b32_e32 v52, v136
	v_mov_b32_e32 v53, v137
	s_nop 0
	v_mov_b32_e32 v54, v130
	v_mov_b32_e32 v55, v131
	v_mov_b32_e32 v56, v132
	v_mov_b32_e32 v57, v133
	v_mov_b32_e32 v58, v150
	v_mov_b32_e32 v59, v151
	v_mov_b32_e32 v60, v152
	v_mov_b32_e32 v61, v153
	v_mov_b32_e32 v62, v146
	v_mov_b32_e32 v63, v147
	v_mov_b32_e32 v64, v148
	v_mov_b32_e32 v65, v149
	v_pk_mul_f32 v[66:67], v[8:9], v[8:9]
	v_pk_mul_f32 v[68:69], v[106:107], v[106:107]
	v_mov_b32_e32 v80, v66
	v_mov_b32_e32 v81, v102
	v_mov_b32_e32 v102, v67
	v_pk_fma_f32 v[66:67], v[104:105], v[104:105], v[68:69]
	v_mov_b32_e32 v78, v110
	v_pk_fma_f32 v[66:67], v[108:109], v[108:109], v[66:67]
	v_mov_b32_e32 v79, v100
	v_pk_fma_f32 v[66:67], v[112:113], v[112:113], v[66:67]
	v_mov_b32_e32 v100, v111
	v_pk_fma_f32 v[66:67], v[114:115], v[114:115], v[66:67]
	s_nop 0
	v_pk_fma_f32 v[66:67], v[116:117], v[116:117], v[66:67]
	s_nop 0
	v_pk_fma_f32 v[66:67], v[118:119], v[118:119], v[66:67]
	s_nop 0
	v_pk_fma_f32 v[66:67], v[120:121], v[120:121], v[66:67]
	s_nop 0
	v_pk_fma_f32 v[66:67], v[122:123], v[122:123], v[66:67]
	s_nop 0
	v_pk_fma_f32 v[66:67], v[124:125], v[124:125], v[66:67]
	s_nop 0
	v_pk_fma_f32 v[66:67], v[126:127], v[126:127], v[66:67]
	s_nop 0
	v_pk_fma_f32 v[66:67], v[128:129], v[128:129], v[66:67]
	s_nop 0
	v_pk_add_f32 v[66:67], v[78:79], v[66:67]
	s_nop 0
	v_pk_add_f32 v[66:67], v[100:101], v[66:67]
	s_nop 0
	v_pk_add_f32 v[66:67], v[80:81], v[66:67]
	s_nop 0
	v_pk_add_f32 v[66:67], v[102:103], v[66:67]
	v_mov_b32_e32 v200, v67
	v_mov_b32_e32 v201, v67
	s_nop 1
	v_permlane32_swap_b32 v200, v201
	v_cndmask_b32_e64 v69, v201, v200, s[40:41]
	v_mov_b32_e32 v200, v66
	v_mov_b32_e32 v201, v66
	s_nop 1
	v_permlane32_swap_b32 v200, v201
	v_cndmask_b32_e64 v68, v201, v200, s[40:41]
	s_waitcnt lgkmcnt(0)
	v_pk_add_f32 v[66:67], v[66:67], v[68:69]
	v_mov_b32_e32 v200, v67
	v_mov_b32_e32 v201, v67
	s_nop 1
	v_permlane16_swap_b32 v200, v201
	v_cndmask_b32_e64 v69, v201, v200, s[42:43]
	v_mov_b32_e32 v200, v66
	v_mov_b32_e32 v201, v66
	s_nop 1
	v_permlane16_swap_b32 v200, v201
	v_cndmask_b32_e64 v68, v201, v200, s[42:43]
	s_waitcnt lgkmcnt(0)
	v_pk_add_f32 v[66:67], v[66:67], v[68:69]
	s_nop 1
	v_mov_b32_dpp v69, v67 row_ror:8 row_mask:0xf bank_mask:0xf
	s_nop 1
	v_mov_b32_dpp v68, v66 row_ror:8 row_mask:0xf bank_mask:0xf
	s_waitcnt lgkmcnt(0)
	v_pk_add_f32 v[66:67], v[66:67], v[68:69]
	s_nop 1
	v_mov_b32_dpp v69, v67 row_shl:4 row_mask:0xf bank_mask:0x5
	v_mov_b32_dpp v69, v67 row_shr:4 row_mask:0xf bank_mask:0xa
	s_nop 1
	v_mov_b32_dpp v68, v66 row_shl:4 row_mask:0xf bank_mask:0x5
	v_mov_b32_dpp v68, v66 row_shr:4 row_mask:0xf bank_mask:0xa
	s_waitcnt lgkmcnt(0)
	v_pk_add_f32 v[66:67], v[66:67], v[68:69]
	s_nop 1
	v_mov_b32_dpp v69, v67 quad_perm:[2,3,0,1] row_mask:0xf bank_mask:0xf
	s_nop 1
	v_mov_b32_dpp v68, v66 quad_perm:[2,3,0,1] row_mask:0xf bank_mask:0xf
	s_waitcnt lgkmcnt(0)
	v_pk_add_f32 v[66:67], v[66:67], v[68:69]
	s_nop 1
	v_mov_b32_dpp v69, v67 quad_perm:[1,0,3,2] row_mask:0xf bank_mask:0xf
	s_nop 1
	v_mov_b32_dpp v68, v66 quad_perm:[1,0,3,2] row_mask:0xf bank_mask:0xf
	s_waitcnt lgkmcnt(0)
	v_pk_add_f32 v[66:67], v[66:67], v[68:69]
	s_nop 0
	v_pk_fma_f32 v[66:67], v[66:67], s[18:19], v[36:37] op_sel_hi:[1,0,0]
	v_lshl_add_u64 v[68:69], v[28:29], 0, v[48:49]
	v_mul_f32_e32 v19, 0x4b800000, v67
	v_cmp_gt_f32_e32 vcc, s22, v67
	s_nop 1
	v_cndmask_b32_e32 v19, v67, v19, vcc
	v_rsq_f32_e32 v19, v19
	s_nop 0
	v_mul_f32_e32 v67, 0x45800000, v19
	v_cndmask_b32_e32 v70, v19, v67, vcc
	v_pk_mul_f32 v[78:79], v[84:85], v[70:71] op_sel_hi:[1,0]
	v_pk_mul_f32 v[80:81], v[88:89], v[70:71] op_sel_hi:[1,0]
	v_pk_mul_f32 v[82:83], v[86:87], v[70:71] op_sel_hi:[1,0]
	v_pk_mul_f32 v[84:85], v[90:91], v[70:71] op_sel_hi:[1,0]
	s_waitcnt vmcnt(1)
	v_pk_fma_f32 v[78:79], v[54:55], v[78:79], v[62:63]
	v_pk_fma_f32 v[80:81], v[50:51], v[80:81], v[58:59]
	v_pk_fma_f32 v[82:83], v[56:57], v[82:83], v[64:65]
	v_pk_fma_f32 v[84:85], v[52:53], v[84:85], v[60:61]
	v_cvt_pk_bf16_f32 v50, v78, v79
	v_cvt_pk_bf16_f32 v51, v82, v83
	v_cvt_pk_bf16_f32 v52, v80, v81
	v_cvt_pk_bf16_f32 v53, v84, v85
	global_store_dwordx4 v[68:69], v[50:53], off
	global_load_dwordx4 v[50:53], v[42:43], off
	s_nop 0
	global_load_dwordx4 v[54:57], v[42:43], off offset:16
	global_load_dwordx4 v[58:61], v[44:45], off
	global_load_dwordx4 v[62:65], v[44:45], off offset:16
	v_lshl_add_u64 v[86:87], v[30:31], 0, v[48:49]
	v_mul_f32_e32 v19, 0x4b800000, v66
	v_cmp_gt_f32_e32 vcc, s22, v66
	s_waitcnt vmcnt(3)
	v_pk_add_f32 v[48:49], v[50:51], 1.0 op_sel_hi:[1,0]
	s_waitcnt vmcnt(2)
	v_pk_add_f32 v[50:51], v[54:55], 1.0 op_sel_hi:[1,0]
	v_pk_add_f32 v[52:53], v[52:53], 1.0 op_sel_hi:[1,0]
	v_pk_add_f32 v[54:55], v[56:57], 1.0 op_sel_hi:[1,0]
	s_waitcnt vmcnt(1)
	v_pk_fma_f32 v[48:49], v[48:49], v[78:79], v[58:59]
	s_waitcnt vmcnt(0)
	v_pk_fma_f32 v[50:51], v[50:51], v[80:81], v[62:63]
	v_pk_fma_f32 v[52:53], v[52:53], v[82:83], v[60:61]
	v_pk_fma_f32 v[54:55], v[54:55], v[84:85], v[64:65]
	v_cvt_pk_bf16_f32 v48, v48, v49
	v_cvt_pk_bf16_f32 v49, v52, v53
	v_cvt_pk_bf16_f32 v50, v50, v51
	v_cvt_pk_bf16_f32 v51, v54, v55
	global_store_dwordx4 v[86:87], v[48:51], off
	s_nop 1
	v_mov_b32_e32 v48, v142
	v_mov_b32_e32 v49, v143
	v_mov_b32_e32 v50, v144
	v_mov_b32_e32 v51, v145
	s_nop 0
	v_mov_b32_e32 v52, v138
	v_mov_b32_e32 v53, v139
	v_mov_b32_e32 v54, v140
	v_mov_b32_e32 v55, v141
	v_mov_b32_e32 v56, v154
	v_mov_b32_e32 v57, v155
	v_mov_b32_e32 v58, v156
	v_mov_b32_e32 v59, v157
	v_mov_b32_e32 v60, v158
	v_mov_b32_e32 v61, v159
	v_mov_b32_e32 v62, v160
	v_mov_b32_e32 v63, v161
	v_pk_mul_f32 v[64:65], v[92:93], v[70:71] op_sel_hi:[1,0]
	v_pk_mul_f32 v[78:79], v[96:97], v[70:71] op_sel_hi:[1,0]
	v_pk_mul_f32 v[80:81], v[94:95], v[70:71] op_sel_hi:[1,0]
	v_pk_mul_f32 v[82:83], v[98:99], v[70:71] op_sel_hi:[1,0]
	v_cndmask_b32_e32 v19, v66, v19, vcc
	v_rsq_f32_e32 v19, v19
	s_waitcnt vmcnt(1)
	v_pk_fma_f32 v[64:65], v[52:53], v[64:65], v[56:57]
	s_waitcnt vmcnt(1)
	v_pk_fma_f32 v[78:79], v[48:49], v[78:79], v[60:61]
	v_pk_fma_f32 v[80:81], v[54:55], v[80:81], v[58:59]
	v_pk_fma_f32 v[82:83], v[50:51], v[82:83], v[62:63]
	v_cvt_pk_bf16_f32 v48, v64, v65
	v_cvt_pk_bf16_f32 v49, v80, v81
	v_cvt_pk_bf16_f32 v50, v78, v79
	v_cvt_pk_bf16_f32 v51, v82, v83
	global_store_dwordx4 v[68:69], v[48:51], off offset:1024
	global_load_dwordx4 v[48:51], v[40:41], off
	s_nop 0
	global_load_dwordx4 v[52:55], v[40:41], off offset:16
	global_load_dwordx4 v[56:59], v[46:47], off
	global_load_dwordx4 v[60:63], v[46:47], off offset:16
	v_mul_f32_e32 v66, 0x45800000, v19
	v_cndmask_b32_e32 v66, v19, v66, vcc
	v_pk_mul_f32 v[10:11], v[10:11], v[66:67] op_sel_hi:[1,0]
	v_pk_mul_f32 v[16:17], v[16:17], v[66:67] op_sel_hi:[1,0]
	v_pk_mul_f32 v[12:13], v[12:13], v[66:67] op_sel_hi:[1,0]
	v_pk_mul_f32 v[14:15], v[14:15], v[66:67] op_sel_hi:[1,0]
	v_pk_mul_f32 v[4:5], v[4:5], v[66:67] op_sel_hi:[1,0]
	v_pk_mul_f32 v[6:7], v[6:7], v[66:67] op_sel_hi:[1,0]
	v_pk_mul_f32 v[2:3], v[2:3], v[66:67] op_sel_hi:[1,0]
	v_pk_mul_f32 v[8:9], v[8:9], v[66:67] op_sel_hi:[1,0]
	v_cmp_lt_i32_e32 vcc, s23, v18
	s_or_b64 s[4:5], vcc, s[4:5]
	s_waitcnt vmcnt(3)
	v_pk_add_f32 v[48:49], v[48:49], 1.0 op_sel_hi:[1,0]
	s_waitcnt vmcnt(2)
	v_pk_add_f32 v[52:53], v[52:53], 1.0 op_sel_hi:[1,0]
	v_pk_add_f32 v[50:51], v[50:51], 1.0 op_sel_hi:[1,0]
	v_pk_add_f32 v[54:55], v[54:55], 1.0 op_sel_hi:[1,0]
	s_waitcnt vmcnt(1)
	v_pk_fma_f32 v[48:49], v[48:49], v[64:65], v[56:57]
	s_waitcnt vmcnt(0)
	v_pk_fma_f32 v[52:53], v[52:53], v[78:79], v[60:61]
	v_pk_fma_f32 v[50:51], v[50:51], v[80:81], v[58:59]
	v_pk_fma_f32 v[54:55], v[54:55], v[82:83], v[62:63]
	v_cvt_pk_bf16_f32 v48, v48, v49
	v_cvt_pk_bf16_f32 v49, v50, v51
	v_cvt_pk_bf16_f32 v50, v52, v53
	v_cvt_pk_bf16_f32 v51, v54, v55
	global_store_dwordx4 v[86:87], v[48:51], off offset:1024
	s_nop 1
	v_mov_b32_e32 v48, v134
	v_mov_b32_e32 v49, v135
	v_mov_b32_e32 v50, v136
	v_mov_b32_e32 v51, v137
	s_nop 0
	v_mov_b32_e32 v52, v130
	v_mov_b32_e32 v53, v131
	v_mov_b32_e32 v54, v132
	v_mov_b32_e32 v55, v133
	v_mov_b32_e32 v56, v146
	v_mov_b32_e32 v57, v147
	v_mov_b32_e32 v58, v148
	v_mov_b32_e32 v59, v149
	v_mov_b32_e32 v60, v150
	v_mov_b32_e32 v61, v151
	v_mov_b32_e32 v62, v152
	v_mov_b32_e32 v63, v153
	v_lshl_add_u64 v[64:65], v[28:29], 0, v[38:39]
	v_lshl_add_u64 v[38:39], v[30:31], 0, v[38:39]
	s_waitcnt vmcnt(1)
	v_pk_fma_f32 v[56:57], v[52:53], v[10:11], v[56:57]
	s_waitcnt vmcnt(1)
	v_pk_fma_f32 v[60:61], v[48:49], v[16:17], v[60:61]
	v_pk_fma_f32 v[58:59], v[54:55], v[12:13], v[58:59]
	v_pk_fma_f32 v[62:63], v[50:51], v[14:15], v[62:63]
	v_cvt_pk_bf16_f32 v10, v56, v57
	v_cvt_pk_bf16_f32 v11, v58, v59
	v_cvt_pk_bf16_f32 v12, v60, v61
	v_cvt_pk_bf16_f32 v13, v62, v63
	global_store_dwordx4 v[64:65], v[10:13], off
	global_load_dwordx4 v[10:13], v[42:43], off
	s_nop 0
	global_load_dwordx4 v[14:17], v[42:43], off offset:16
	global_load_dwordx4 v[48:51], v[44:45], off
	global_load_dwordx4 v[52:55], v[44:45], off offset:16
	s_waitcnt vmcnt(3)
	v_pk_add_f32 v[10:11], v[10:11], 1.0 op_sel_hi:[1,0]
	s_waitcnt vmcnt(2)
	v_pk_add_f32 v[14:15], v[14:15], 1.0 op_sel_hi:[1,0]
	v_pk_add_f32 v[12:13], v[12:13], 1.0 op_sel_hi:[1,0]
	v_pk_add_f32 v[16:17], v[16:17], 1.0 op_sel_hi:[1,0]
	s_waitcnt vmcnt(1)
	v_pk_fma_f32 v[10:11], v[10:11], v[56:57], v[48:49]
	s_waitcnt vmcnt(0)
	v_pk_fma_f32 v[14:15], v[14:15], v[60:61], v[52:53]
	v_pk_fma_f32 v[12:13], v[12:13], v[58:59], v[50:51]
	v_pk_fma_f32 v[16:17], v[16:17], v[62:63], v[54:55]
	v_cvt_pk_bf16_f32 v10, v10, v11
	v_cvt_pk_bf16_f32 v11, v12, v13
	v_cvt_pk_bf16_f32 v12, v14, v15
	v_cvt_pk_bf16_f32 v13, v16, v17
	global_store_dwordx4 v[38:39], v[10:13], off
	s_nop 1
	v_mov_b32_e32 v10, v142
	v_mov_b32_e32 v11, v143
	v_mov_b32_e32 v12, v144
	v_mov_b32_e32 v13, v145
	s_nop 0
	v_mov_b32_e32 v14, v138
	v_mov_b32_e32 v15, v139
	v_mov_b32_e32 v16, v140
	v_mov_b32_e32 v17, v141
	v_mov_b32_e32 v42, v154
	v_mov_b32_e32 v43, v155
	v_mov_b32_e32 v44, v156
	v_mov_b32_e32 v45, v157
	v_mov_b32_e32 v48, v158
	v_mov_b32_e32 v49, v159
	v_mov_b32_e32 v50, v160
	v_mov_b32_e32 v51, v161
	s_waitcnt vmcnt(1)
	v_pk_fma_f32 v[42:43], v[14:15], v[4:5], v[42:43]
	s_waitcnt vmcnt(1)
	v_pk_fma_f32 v[48:49], v[10:11], v[6:7], v[48:49]
	v_pk_fma_f32 v[44:45], v[16:17], v[2:3], v[44:45]
	v_pk_fma_f32 v[50:51], v[12:13], v[8:9], v[50:51]
	v_cvt_pk_bf16_f32 v2, v42, v43
	v_cvt_pk_bf16_f32 v3, v44, v45
	v_cvt_pk_bf16_f32 v4, v48, v49
	v_cvt_pk_bf16_f32 v5, v50, v51
	global_store_dwordx4 v[64:65], v[2:5], off offset:1024
	global_load_dwordx4 v[2:5], v[40:41], off
	s_nop 0
	global_load_dwordx4 v[6:9], v[40:41], off offset:16
	global_load_dwordx4 v[10:13], v[46:47], off
	global_load_dwordx4 v[14:17], v[46:47], off offset:16
	s_waitcnt vmcnt(3)
	v_pk_add_f32 v[2:3], v[2:3], 1.0 op_sel_hi:[1,0]
	s_waitcnt vmcnt(2)
	v_pk_add_f32 v[6:7], v[6:7], 1.0 op_sel_hi:[1,0]
	v_pk_add_f32 v[4:5], v[4:5], 1.0 op_sel_hi:[1,0]
	v_pk_add_f32 v[8:9], v[8:9], 1.0 op_sel_hi:[1,0]
	s_waitcnt vmcnt(1)
	v_pk_fma_f32 v[2:3], v[2:3], v[42:43], v[10:11]
	s_waitcnt vmcnt(0)
	v_pk_fma_f32 v[6:7], v[6:7], v[48:49], v[14:15]
	v_pk_fma_f32 v[4:5], v[4:5], v[44:45], v[12:13]
	v_pk_fma_f32 v[8:9], v[8:9], v[50:51], v[16:17]
	v_cvt_pk_bf16_f32 v2, v2, v3
	v_cvt_pk_bf16_f32 v3, v4, v5
	v_cvt_pk_bf16_f32 v4, v6, v7
	v_cvt_pk_bf16_f32 v5, v8, v9
	global_store_dwordx4 v[38:39], v[2:5], off offset:1024
	s_andn2_b64 exec, exec, s[4:5]
	s_cbranch_execnz .LBB0_1364

.LBB0_1616:
	s_cmp_lt_i32 s68, 15
	s_cselect_b64 s[6:7], -1, 0
	s_and_b64 s[4:5], s[6:7], s[4:5]
	s_andn2_b64 vcc, exec, s[4:5]
	s_cbranch_vccnz .LBB0_1620
	v_and_b32_e32 v0, 60, v206
	v_lshl_add_u32 v4, s2, 5, v0
	s_movk_i32 s2, 0x4000
	v_cmp_gt_i32_e32 vcc, s2, v4
	s_and_saveexec_b64 s[2:3], vcc
	s_cbranch_execz .LBB0_1620
	v_lshlrev_b32_e32 v0, 3, v1
	v_and_b32_e32 v5, 0x1f8, v0
	v_lshlrev_b32_e32 v0, 1, v5
	v_mov_b32_e32 v1, 0
	s_load_dwordx4 s[4:7], s[0:1], 0xe0
	v_lshl_add_u64 v[2:3], s[66:67], 0, v[0:1]
	s_mov_b64 s[0:1], 0x1c00000
	v_lshl_add_u64 v[6:7], v[2:3], 0, s[0:1]
	v_mbcnt_lo_u32_b32 v2, -1, 0
	v_mbcnt_hi_u32_b32 v2, -1, v2
	v_and_b32_e32 v3, 64, v2
	v_lshlrev_b32_e32 v0, 2, v5
	v_add_u32_e32 v3, 64, v3
	v_xor_b32_e32 v5, 32, v2
	v_cmp_lt_i32_e32 vcc, v5, v3
	s_waitcnt lgkmcnt(0)
	v_lshl_add_u64 v[8:9], s[4:5], 0, v[0:1]
	s_mov_b32 s4, 0x3727c5ac
	v_cndmask_b32_e32 v5, v2, v5, vcc
	v_lshlrev_b32_e32 v48, 2, v5
	v_xor_b32_e32 v5, 16, v2
	v_cmp_lt_i32_e32 vcc, v5, v3
	s_lshl_b32 s3, s70, 5
	v_lshl_add_u64 v[10:11], s[6:7], 0, v[0:1]
	v_cndmask_b32_e32 v5, v2, v5, vcc
	v_lshlrev_b32_e32 v49, 2, v5
	v_xor_b32_e32 v5, 8, v2
	v_cmp_lt_i32_e32 vcc, v5, v3
	v_lshl_add_u64 v[12:13], s[64:65], 0, v[0:1]
	s_mov_b64 s[0:1], 0
	v_cndmask_b32_e32 v5, v2, v5, vcc
	v_lshlrev_b32_e32 v50, 2, v5
	v_xor_b32_e32 v5, 4, v2
	v_cmp_lt_i32_e32 vcc, v5, v3
	s_mov_b32 s2, 0x3a800000
	v_mov_b64_e32 v[14:15], s[4:5]
	v_cndmask_b32_e32 v5, v2, v5, vcc
	v_lshlrev_b32_e32 v51, 2, v5
	v_xor_b32_e32 v5, 2, v2
	v_cmp_lt_i32_e32 vcc, v5, v3
	s_mov_b32 s4, 0x800000
	s_movk_i32 s5, 0x3fff
	v_cndmask_b32_e32 v5, v2, v5, vcc
	v_lshlrev_b32_e32 v52, 2, v5
	v_xor_b32_e32 v5, 1, v2
	v_cmp_lt_i32_e32 vcc, v5, v3
	s_nop 1
	v_cndmask_b32_e32 v2, v2, v5, vcc
	v_lshlrev_b32_e32 v53, 2, v2
	global_load_dwordx4 v[112:115], v[10:11], off
	global_load_dwordx4 v[116:119], v[10:11], off offset:16
	global_load_dwordx4 v[120:123], v[10:11], off offset:2048
	global_load_dwordx4 v[124:127], v[10:11], off offset:2064
	global_load_dwordx4 v[128:131], v[8:9], off
	global_load_dwordx4 v[132:135], v[8:9], off offset:16
	global_load_dwordx4 v[136:139], v[8:9], off offset:2048
	global_load_dwordx4 v[140:143], v[8:9], off offset:2064
	s_mov_b64 s[14:15], 0x1000
	v_mov_b32_e32 v192, v4
	v_ashrrev_i32_e32 v193, 31, v192
	v_lshlrev_b64 v[194:195], 11, v[192:193]
	v_lshl_add_u64 v[194:195], v[6:7], 0, v[194:195]
	v_lshl_add_u64 v[196:197], v[194:195], 0, s[14:15]
	global_load_dwordx4 v[144:147], v[194:195], off
	global_load_dwordx4 v[148:151], v[194:195], off offset:1024
	global_load_dwordx4 v[152:155], v[194:195], off offset:2048
	global_load_dwordx4 v[156:159], v[194:195], off offset:3072
	global_load_dwordx4 v[160:163], v[196:197], off
	global_load_dwordx4 v[164:167], v[196:197], off offset:1024
	global_load_dwordx4 v[168:171], v[196:197], off offset:2048
	global_load_dwordx4 v[172:175], v[196:197], off offset:3072
	s_waitcnt vmcnt(0)
	s_mov_b32 s20, 0
	s_mov_b32 s21, -1
	s_mov_b32 s22, 0xffff0000
	s_mov_b32 s23, 0xffff0000
.LBB0_1619:
	v_ashrrev_i32_e32 v5, 31, v4
	v_lshlrev_b64 v[0:1], 11, v[4:5]
	v_add_u32_e32 v36, 1, v4
	v_lshl_add_u64 v[20:21], v[6:7], 0, v[0:1]
	v_ashrrev_i32_e32 v37, 31, v36
	v_lshlrev_b64 v[20:21], 11, v[36:37]
	v_lshl_add_u64 v[28:29], v[6:7], 0, v[20:21]
	v_mov_b32_e32 v54, v132
	v_mov_b32_e32 v55, v133
	v_mov_b32_e32 v56, v134
	v_mov_b32_e32 v57, v135
	v_mov_b32_e32 v58, v128
	v_mov_b32_e32 v59, v129
	v_mov_b32_e32 v60, v130
	v_mov_b32_e32 v61, v131
	v_mov_b32_e32 v62, v116
	v_mov_b32_e32 v63, v117
	v_mov_b32_e32 v64, v118
	v_mov_b32_e32 v65, v119
	v_mov_b32_e32 v66, v112
	v_mov_b32_e32 v67, v113
	v_mov_b32_e32 v68, v114
	v_mov_b32_e32 v69, v115
	v_lshlrev_b64 v[36:37], 12, v[36:37]
	v_lshl_add_u64 v[36:37], v[12:13], 0, v[36:37]
	s_waitcnt vmcnt(16)
	v_mov_b32_e32 v0, v144
	v_mov_b32_e32 v1, v145
	v_mov_b32_e32 v2, v146
	v_mov_b32_e32 v3, v147
	v_mov_b32_e32 v16, v148
	v_mov_b32_e32 v17, v149
	v_mov_b32_e32 v18, v150
	v_mov_b32_e32 v19, v151
	v_mov_b32_e32 v20, v152
	v_mov_b32_e32 v21, v153
	v_mov_b32_e32 v22, v154
	v_mov_b32_e32 v23, v155
	v_mov_b32_e32 v24, v156
	v_mov_b32_e32 v25, v157
	v_mov_b32_e32 v26, v158
	v_mov_b32_e32 v27, v159
	v_lshlrev_b32_e32 v30, 16, v0
	v_and_b32_e32 v31, 0xffff0000, v0
	v_add_f32_e32 v40, 0, v30
	v_lshlrev_b32_e32 v70, 16, v20
	v_lshlrev_b32_e32 v0, 16, v1
	v_and_b32_e32 v71, 0xffff0000, v20
	v_add_f32_e32 v40, v40, v31
	v_add_f32_e32 v41, 0, v70
	v_and_b32_e32 v1, 0xffff0000, v1
	v_lshlrev_b32_e32 v20, 16, v21
	v_add_f32_e32 v40, v40, v0
	v_add_f32_e32 v41, v41, v71
	v_lshlrev_b32_e32 v28, 16, v2
	v_and_b32_e32 v21, 0xffff0000, v21
	v_add_f32_e32 v40, v40, v1
	v_add_f32_e32 v41, v41, v20
	v_and_b32_e32 v29, 0xffff0000, v2
	v_lshlrev_b32_e32 v38, 16, v22
	v_add_f32_e32 v40, v40, v28
	v_add_f32_e32 v41, v41, v21
	v_lshlrev_b32_e32 v2, 16, v3
	v_and_b32_e32 v39, 0xffff0000, v22
	v_add_f32_e32 v40, v40, v29
	v_add_f32_e32 v41, v41, v38
	v_and_b32_e32 v3, 0xffff0000, v3
	v_lshlrev_b32_e32 v22, 16, v23
	v_add_f32_e32 v40, v40, v2
	v_add_f32_e32 v41, v41, v39
	v_lshlrev_b32_e32 v34, 16, v16
	v_and_b32_e32 v23, 0xffff0000, v23
	v_add_f32_e32 v40, v40, v3
	v_add_f32_e32 v41, v41, v22
	v_and_b32_e32 v35, 0xffff0000, v16
	v_lshlrev_b32_e32 v74, 16, v24
	v_add_f32_e32 v40, v40, v34
	v_add_f32_e32 v41, v41, v23
	v_lshlrev_b32_e32 v16, 16, v17
	v_and_b32_e32 v75, 0xffff0000, v24
	v_add_f32_e32 v40, v40, v35
	v_add_f32_e32 v41, v41, v74
	v_and_b32_e32 v17, 0xffff0000, v17
	v_lshlrev_b32_e32 v24, 16, v25
	v_add_f32_e32 v40, v40, v16
	v_add_f32_e32 v41, v41, v75
	v_lshlrev_b32_e32 v32, 16, v18
	v_and_b32_e32 v25, 0xffff0000, v25
	v_add_f32_e32 v40, v40, v17
	v_add_f32_e32 v41, v41, v24
	v_and_b32_e32 v33, 0xffff0000, v18
	v_lshlrev_b32_e32 v72, 16, v26
	v_add_f32_e32 v40, v40, v32
	v_add_f32_e32 v41, v41, v25
	v_lshlrev_b32_e32 v18, 16, v19
	v_and_b32_e32 v73, 0xffff0000, v26
	v_add_f32_e32 v40, v40, v33
	v_add_f32_e32 v41, v41, v72
	v_and_b32_e32 v19, 0xffff0000, v19
	v_lshlrev_b32_e32 v26, 16, v27
	v_add_f32_e32 v40, v40, v18
	v_add_f32_e32 v41, v41, v73
	v_and_b32_e32 v27, 0xffff0000, v27
	v_add_f32_e32 v40, v40, v19
	v_add_f32_e32 v41, v41, v26
	v_mov_b32_e32 v200, v40
	v_mov_b32_e32 v201, v40
	s_nop 1
	v_permlane32_swap_b32 v200, v201
	v_cndmask_b32_e64 v42, v201, v200, s[20:21]
	v_add_f32_e32 v41, v41, v27
	v_mov_b32_e32 v200, v41
	v_mov_b32_e32 v201, v41
	s_nop 1
	v_permlane32_swap_b32 v200, v201
	v_cndmask_b32_e64 v43, v201, v200, s[20:21]
	s_waitcnt lgkmcnt(1)
	v_add_f32_e32 v40, v40, v42
	v_mov_b32_e32 v200, v40
	v_mov_b32_e32 v201, v40
	s_nop 1
	v_permlane16_swap_b32 v200, v201
	v_cndmask_b32_e64 v42, v201, v200, s[22:23]
	s_waitcnt lgkmcnt(1)
	v_add_f32_e32 v41, v41, v43
	v_mov_b32_e32 v200, v41
	v_mov_b32_e32 v201, v41
	s_nop 1
	v_permlane16_swap_b32 v200, v201
	v_cndmask_b32_e64 v43, v201, v200, s[22:23]
	s_waitcnt lgkmcnt(1)
	v_add_f32_e32 v40, v40, v42
	s_nop 1
	v_mov_b32_dpp v42, v40 row_ror:8 row_mask:0xf bank_mask:0xf
	s_waitcnt lgkmcnt(1)
	v_add_f32_e32 v41, v41, v43
	s_nop 1
	v_mov_b32_dpp v43, v41 row_ror:8 row_mask:0xf bank_mask:0xf
	s_waitcnt lgkmcnt(1)
	v_add_f32_e32 v40, v40, v42
	s_nop 1
	v_mov_b32_dpp v42, v40 row_shl:4 row_mask:0xf bank_mask:0x5
	v_mov_b32_dpp v42, v40 row_shr:4 row_mask:0xf bank_mask:0xa
	s_waitcnt lgkmcnt(1)
	v_add_f32_e32 v41, v41, v43
	s_nop 1
	v_mov_b32_dpp v43, v41 row_shl:4 row_mask:0xf bank_mask:0x5
	v_mov_b32_dpp v43, v41 row_shr:4 row_mask:0xf bank_mask:0xa
	s_waitcnt lgkmcnt(1)
	v_add_f32_e32 v40, v40, v42
	s_nop 1
	v_mov_b32_dpp v42, v40 quad_perm:[2,3,0,1] row_mask:0xf bank_mask:0xf
	s_waitcnt lgkmcnt(1)
	v_add_f32_e32 v41, v41, v43
	s_nop 1
	v_mov_b32_dpp v43, v41 quad_perm:[2,3,0,1] row_mask:0xf bank_mask:0xf
	s_waitcnt lgkmcnt(1)
	v_add_f32_e32 v40, v40, v42
	s_nop 1
	v_mov_b32_dpp v42, v40 quad_perm:[1,0,3,2] row_mask:0xf bank_mask:0xf
	s_waitcnt lgkmcnt(1)
	v_add_f32_e32 v41, v41, v43
	s_nop 1
	v_mov_b32_dpp v43, v41 quad_perm:[1,0,3,2] row_mask:0xf bank_mask:0xf
	s_waitcnt lgkmcnt(1)
	v_add_f32_e32 v40, v40, v42
	v_mul_f32_e32 v46, 0x3a800000, v40
	s_waitcnt lgkmcnt(0)
	v_add_f32_e32 v76, v41, v43
	v_pk_add_f32 v[84:85], v[0:1], v[46:47] op_sel_hi:[1,0] neg_lo:[0,1] neg_hi:[0,1]
	v_mul_f32_e32 v0, 0x3a800000, v76
	v_pk_add_f32 v[82:83], v[30:31], v[46:47] op_sel_hi:[1,0] neg_lo:[0,1] neg_hi:[0,1]
	v_pk_add_f32 v[86:87], v[28:29], v[46:47] op_sel_hi:[1,0] neg_lo:[0,1] neg_hi:[0,1]
	v_pk_add_f32 v[28:29], v[70:71], v[0:1] op_sel_hi:[1,0] neg_lo:[0,1] neg_hi:[0,1]
	v_mov_b32_e32 v77, v83
	v_mov_b32_e32 v76, v29
	v_mov_b32_e32 v71, v82
	v_pk_add_f32 v[30:31], v[20:21], v[0:1] op_sel_hi:[1,0] neg_lo:[0,1] neg_hi:[0,1]
	v_mov_b32_e32 v70, v28
	v_pk_mul_f32 v[76:77], v[76:77], v[76:77]
	v_mov_b32_e32 v79, v84
	v_mov_b32_e32 v78, v30
	v_pk_fma_f32 v[70:71], v[70:71], v[70:71], v[76:77]
	v_pk_add_f32 v[40:41], v[34:35], v[46:47] op_sel_hi:[1,0] neg_lo:[0,1] neg_hi:[0,1]
	v_pk_add_f32 v[42:43], v[32:33], v[46:47] op_sel_hi:[1,0] neg_lo:[0,1] neg_hi:[0,1]
	v_pk_add_f32 v[32:33], v[38:39], v[0:1] op_sel_hi:[1,0] neg_lo:[0,1] neg_hi:[0,1]
	v_pk_add_f32 v[34:35], v[22:23], v[0:1] op_sel_hi:[1,0] neg_lo:[0,1] neg_hi:[0,1]
	v_pk_add_f32 v[22:23], v[24:25], v[0:1] op_sel_hi:[1,0] neg_lo:[0,1] neg_hi:[0,1]
	v_mov_b32_e32 v25, v85
	v_mov_b32_e32 v24, v31
	v_pk_fma_f32 v[70:71], v[78:79], v[78:79], v[70:71]
	v_mov_b32_e32 v39, v86
	v_mov_b32_e32 v38, v32
	v_pk_fma_f32 v[24:25], v[24:25], v[24:25], v[70:71]
	v_pk_add_f32 v[88:89], v[2:3], v[46:47] op_sel_hi:[1,0] neg_lo:[0,1] neg_hi:[0,1]
	v_pk_add_f32 v[20:21], v[72:73], v[0:1] op_sel_hi:[1,0] neg_lo:[0,1] neg_hi:[0,1]
	v_mov_b32_e32 v73, v87
	v_mov_b32_e32 v72, v33
	v_pk_fma_f32 v[24:25], v[38:39], v[38:39], v[24:25]
	v_pk_add_f32 v[44:45], v[16:17], v[46:47] op_sel_hi:[1,0] neg_lo:[0,1] neg_hi:[0,1]
	v_pk_add_f32 v[46:47], v[18:19], v[46:47] op_sel_hi:[1,0] neg_lo:[0,1] neg_hi:[0,1]
	v_pk_add_f32 v[18:19], v[74:75], v[0:1] op_sel_hi:[1,0] neg_lo:[0,1] neg_hi:[0,1]
	v_mov_b32_e32 v75, v88
	v_mov_b32_e32 v74, v34
	v_pk_fma_f32 v[24:25], v[72:73], v[72:73], v[24:25]
	v_mov_b32_e32 v81, v89
	v_mov_b32_e32 v80, v35
	v_pk_fma_f32 v[24:25], v[74:75], v[74:75], v[24:25]
	v_mov_b32_e32 v92, v18
	v_pk_fma_f32 v[24:25], v[80:81], v[80:81], v[24:25]
	v_mov_b32_e32 v93, v40
	v_pk_fma_f32 v[24:25], v[92:93], v[92:93], v[24:25]
	v_mov_b32_e32 v38, v19
	v_mov_b32_e32 v39, v41
	v_pk_fma_f32 v[24:25], v[38:39], v[38:39], v[24:25]
	v_mov_b32_e32 v38, v22
	v_mov_b32_e32 v39, v44
	v_pk_mul_f32 v[2:3], v[42:43], v[42:43]
	v_pk_mul_f32 v[90:91], v[20:21], v[20:21]
	v_pk_fma_f32 v[24:25], v[38:39], v[38:39], v[24:25]
	v_mov_b32_e32 v38, v23
	v_mov_b32_e32 v39, v45
	v_pk_fma_f32 v[24:25], v[38:39], v[38:39], v[24:25]
	v_mov_b32_e32 v38, v90
	v_mov_b32_e32 v39, v2
	v_pk_add_f32 v[26:27], v[26:27], v[0:1] op_sel_hi:[1,0] neg_lo:[0,1] neg_hi:[0,1]
	v_pk_mul_f32 v[16:17], v[46:47], v[46:47]
	v_pk_add_f32 v[24:25], v[38:39], v[24:25]
	v_pk_mul_f32 v[0:1], v[26:27], v[26:27]
	v_mov_b32_e32 v2, v91
	v_pk_add_f32 v[2:3], v[2:3], v[24:25]
	v_mov_b32_e32 v24, v0
	v_mov_b32_e32 v25, v16
	v_pk_add_f32 v[2:3], v[24:25], v[2:3]
	v_mov_b32_e32 v16, v1
	v_pk_add_f32 v[0:1], v[16:17], v[2:3]
	v_mov_b32_e32 v200, v1
	v_mov_b32_e32 v201, v1
	s_nop 1
	v_permlane32_swap_b32 v200, v201
	v_cndmask_b32_e64 v3, v201, v200, s[20:21]
	v_mov_b32_e32 v200, v0
	v_mov_b32_e32 v201, v0
	s_nop 1
	v_permlane32_swap_b32 v200, v201
	v_cndmask_b32_e64 v2, v201, v200, s[20:21]
	v_add_u32_e32 v24, 2, v4
	v_ashrrev_i32_e32 v25, 31, v24
	v_lshlrev_b64 v[16:17], 11, v[24:25]
	v_lshl_add_u64 v[16:17], v[6:7], 0, v[16:17]
	s_waitcnt lgkmcnt(0)
	v_pk_add_f32 v[0:1], v[0:1], v[2:3]
	v_mov_b32_e32 v200, v1
	v_mov_b32_e32 v201, v1
	s_nop 1
	v_permlane16_swap_b32 v200, v201
	v_cndmask_b32_e64 v3, v201, v200, s[22:23]
	v_mov_b32_e32 v200, v0
	v_mov_b32_e32 v201, v0
	s_nop 1
	v_permlane16_swap_b32 v200, v201
	v_cndmask_b32_e64 v2, v201, v200, s[22:23]
	v_mov_b32_e32 v70, v160
	v_mov_b32_e32 v71, v161
	v_mov_b32_e32 v72, v162
	v_mov_b32_e32 v73, v163
	v_mov_b32_e32 v74, v164
	v_mov_b32_e32 v75, v165
	v_mov_b32_e32 v76, v166
	v_mov_b32_e32 v77, v167
	v_add_u32_e32 v16, 3, v4
	v_ashrrev_i32_e32 v17, 31, v16
	v_lshlrev_b64 v[38:39], 11, v[16:17]
	s_waitcnt lgkmcnt(0)
	v_pk_add_f32 v[0:1], v[0:1], v[2:3]
	s_nop 1
	v_mov_b32_dpp v3, v1 row_ror:8 row_mask:0xf bank_mask:0xf
	s_nop 1
	v_mov_b32_dpp v2, v0 row_ror:8 row_mask:0xf bank_mask:0xf
	v_lshl_add_u64 v[90:91], v[6:7], 0, v[38:39]
	v_lshlrev_b64 v[16:17], 12, v[16:17]
	s_waitcnt lgkmcnt(0)
	v_pk_add_f32 v[0:1], v[0:1], v[2:3]
	s_nop 1
	v_mov_b32_dpp v3, v1 row_shl:4 row_mask:0xf bank_mask:0x5
	v_mov_b32_dpp v3, v1 row_shr:4 row_mask:0xf bank_mask:0xa
	s_nop 1
	v_mov_b32_dpp v2, v0 row_shl:4 row_mask:0xf bank_mask:0x5
	v_mov_b32_dpp v2, v0 row_shr:4 row_mask:0xf bank_mask:0xa
	s_waitcnt lgkmcnt(0)
	v_pk_add_f32 v[0:1], v[0:1], v[2:3]
	s_nop 1
	v_mov_b32_dpp v3, v1 quad_perm:[2,3,0,1] row_mask:0xf bank_mask:0xf
	s_nop 1
	v_mov_b32_dpp v2, v0 quad_perm:[2,3,0,1] row_mask:0xf bank_mask:0xf
	s_waitcnt lgkmcnt(0)
	v_pk_add_f32 v[0:1], v[0:1], v[2:3]
	s_nop 1
	v_mov_b32_dpp v3, v1 quad_perm:[1,0,3,2] row_mask:0xf bank_mask:0xf
	s_nop 1
	v_mov_b32_dpp v2, v0 quad_perm:[1,0,3,2] row_mask:0xf bank_mask:0xf
	s_waitcnt lgkmcnt(0)
	v_pk_add_f32 v[0:1], v[0:1], v[2:3]
	s_nop 0
	v_pk_fma_f32 v[38:39], v[0:1], s[2:3], v[14:15] op_sel_hi:[1,0,0]
	s_nop 0
	v_mul_f32_e32 v0, 0x4b800000, v39
	v_cmp_gt_f32_e32 vcc, s4, v39
	s_nop 1
	v_cndmask_b32_e32 v0, v39, v0, vcc
	v_rsq_f32_e32 v39, v0
	v_mov_b32_e32 v78, v168
	v_mov_b32_e32 v79, v169
	v_mov_b32_e32 v80, v170
	v_mov_b32_e32 v81, v171
	v_mov_b32_e32 v0, v172
	v_mov_b32_e32 v1, v173
	v_mov_b32_e32 v2, v174
	v_mov_b32_e32 v3, v175
	v_add_u32_e32 v192, s3, v4
	v_cmp_ge_i32_e64 s[8:9], s5, v192
	s_and_saveexec_b64 s[12:13], s[8:9]
	v_ashrrev_i32_e32 v193, 31, v192
	v_lshlrev_b64 v[194:195], 11, v[192:193]
	v_lshl_add_u64 v[194:195], v[6:7], 0, v[194:195]
	v_lshl_add_u64 v[196:197], v[194:195], 0, s[14:15]
	global_load_dwordx4 v[144:147], v[194:195], off
	global_load_dwordx4 v[148:151], v[194:195], off offset:1024
	global_load_dwordx4 v[152:155], v[194:195], off offset:2048
	global_load_dwordx4 v[156:159], v[194:195], off offset:3072
	global_load_dwordx4 v[160:163], v[196:197], off
	global_load_dwordx4 v[164:167], v[196:197], off offset:1024
	global_load_dwordx4 v[168:171], v[196:197], off offset:2048
	global_load_dwordx4 v[172:175], v[196:197], off offset:3072
	s_mov_b64 exec, s[12:13]
	v_lshlrev_b64 v[90:91], 12, v[4:5]
	v_lshl_add_u64 v[90:91], v[12:13], 0, v[90:91]
	v_mul_f32_e32 v5, 0x45800000, v39
	v_cndmask_b32_e32 v92, v39, v5, vcc
	v_pk_mul_f32 v[82:83], v[82:83], v[92:93] op_sel_hi:[1,0]
	v_pk_mul_f32 v[84:85], v[84:85], v[92:93] op_sel_hi:[1,0]
	v_pk_fma_f32 v[58:59], v[58:59], v[82:83], v[66:67]
	v_pk_fma_f32 v[60:61], v[60:61], v[84:85], v[68:69]
	v_pk_mul_f32 v[66:67], v[86:87], v[92:93] op_sel_hi:[1,0]
	v_pk_mul_f32 v[68:69], v[88:89], v[92:93] op_sel_hi:[1,0]
	v_pk_fma_f32 v[54:55], v[54:55], v[66:67], v[62:63]
	v_pk_fma_f32 v[56:57], v[56:57], v[68:69], v[64:65]
	global_store_dwordx4 v[90:91], v[58:61], off
	global_store_dwordx4 v[90:91], v[54:57], off offset:16
	s_nop 1
	v_mov_b32_e32 v54, v120
	v_mov_b32_e32 v55, v121
	v_mov_b32_e32 v56, v122
	v_mov_b32_e32 v57, v123
	s_nop 0
	v_mov_b32_e32 v58, v136
	v_mov_b32_e32 v59, v137
	v_mov_b32_e32 v60, v138
	v_mov_b32_e32 v61, v139
	v_mov_b32_e32 v62, v140
	v_mov_b32_e32 v63, v141
	v_mov_b32_e32 v64, v142
	v_mov_b32_e32 v65, v143
	v_mov_b32_e32 v66, v124
	v_mov_b32_e32 v67, v125
	v_mov_b32_e32 v68, v126
	v_mov_b32_e32 v69, v127
	v_pk_mul_f32 v[44:45], v[44:45], v[92:93] op_sel_hi:[1,0]
	v_pk_mul_f32 v[40:41], v[40:41], v[92:93] op_sel_hi:[1,0]
	v_pk_mul_f32 v[46:47], v[46:47], v[92:93] op_sel_hi:[1,0]
	v_pk_mul_f32 v[84:85], v[42:43], v[92:93] op_sel_hi:[1,0]
	v_cmp_gt_f32_e32 vcc, s4, v38
	v_add_u32_e32 v4, s3, v4
	v_lshlrev_b32_e32 v82, 16, v72
	v_and_b32_e32 v83, 0xffff0000, v72
	v_lshlrev_b32_e32 v72, 16, v74
	v_lshlrev_b32_e32 v92, 16, v1
	v_and_b32_e32 v93, 0xffff0000, v1
	v_lshlrev_b32_e32 v86, 16, v2
	v_and_b32_e32 v87, 0xffff0000, v2
	v_lshlrev_b32_e32 v88, 16, v3
	v_and_b32_e32 v89, 0xffff0000, v3
	v_pk_fma_f32 v[40:41], v[58:59], v[40:41], v[54:55]
	v_pk_fma_f32 v[42:43], v[60:61], v[44:45], v[56:57]
	v_pk_fma_f32 v[44:45], v[62:63], v[84:85], v[66:67]
	v_pk_fma_f32 v[46:47], v[64:65], v[46:47], v[68:69]
	global_store_dwordx4 v[90:91], v[40:43], off offset:2048
	global_store_dwordx4 v[90:91], v[44:47], off offset:2064
	s_nop 0
	v_mov_b32_e32 v40, v132
	v_mov_b32_e32 v41, v133
	v_mov_b32_e32 v42, v134
	v_mov_b32_e32 v43, v135
	s_nop 0
	v_mov_b32_e32 v44, v128
	v_mov_b32_e32 v45, v129
	v_mov_b32_e32 v46, v130
	v_mov_b32_e32 v47, v131
	v_mov_b32_e32 v54, v116
	v_mov_b32_e32 v55, v117
	v_mov_b32_e32 v56, v118
	v_mov_b32_e32 v57, v119
	v_mov_b32_e32 v58, v112
	v_mov_b32_e32 v59, v113
	v_mov_b32_e32 v60, v114
	v_mov_b32_e32 v61, v115
	v_lshlrev_b32_e32 v64, 16, v70
	v_and_b32_e32 v65, 0xffff0000, v70
	v_lshlrev_b32_e32 v90, 16, v0
	v_and_b32_e32 v91, 0xffff0000, v0
	v_add_f32_e32 v0, 0, v64
	v_lshlrev_b32_e32 v66, 16, v71
	v_add_f32_e32 v0, v0, v65
	v_and_b32_e32 v67, 0xffff0000, v71
	v_add_f32_e32 v0, v0, v66
	v_add_f32_e32 v0, v0, v67
	v_add_f32_e32 v0, v0, v82
	v_lshlrev_b32_e32 v62, 16, v73
	v_lshlrev_b32_e32 v84, 16, v78
	v_add_f32_e32 v0, v0, v83
	v_and_b32_e32 v63, 0xffff0000, v73
	v_and_b32_e32 v85, 0xffff0000, v78
	v_add_f32_e32 v1, 0, v84
	v_add_f32_e32 v0, v0, v62
	v_lshlrev_b32_e32 v78, 16, v79
	v_add_f32_e32 v1, v1, v85
	v_add_f32_e32 v0, v0, v63
	v_and_b32_e32 v73, 0xffff0000, v74
	v_and_b32_e32 v79, 0xffff0000, v79
	v_add_f32_e32 v1, v1, v78
	v_add_f32_e32 v0, v0, v72
	v_lshlrev_b32_e32 v68, 16, v76
	v_and_b32_e32 v69, 0xffff0000, v76
	v_lshlrev_b32_e32 v74, 16, v75
	v_lshlrev_b32_e32 v76, 16, v80
	v_add_f32_e32 v1, v1, v79
	v_add_f32_e32 v0, v0, v73
	v_lshlrev_b32_e32 v70, 16, v77
	v_and_b32_e32 v71, 0xffff0000, v77
	v_and_b32_e32 v75, 0xffff0000, v75
	v_and_b32_e32 v77, 0xffff0000, v80
	v_add_f32_e32 v1, v1, v76
	v_add_f32_e32 v0, v0, v74
	v_lshlrev_b32_e32 v80, 16, v81
	v_add_f32_e32 v1, v1, v77
	v_add_f32_e32 v0, v0, v75
	v_and_b32_e32 v81, 0xffff0000, v81
	v_add_f32_e32 v1, v1, v80
	v_add_f32_e32 v0, v0, v68
	v_add_f32_e32 v1, v1, v81
	v_add_f32_e32 v0, v0, v69
	v_add_f32_e32 v1, v1, v90
	v_add_f32_e32 v0, v0, v70
	v_add_f32_e32 v1, v1, v91
	v_add_f32_e32 v0, v0, v71
	v_add_f32_e32 v1, v1, v92
	v_mov_b32_e32 v200, v0
	v_mov_b32_e32 v201, v0
	s_nop 1
	v_permlane32_swap_b32 v200, v201
	v_cndmask_b32_e64 v2, v201, v200, s[20:21]
	v_add_f32_e32 v1, v1, v93
	v_add_f32_e32 v1, v1, v86
	v_add_f32_e32 v1, v1, v87
	v_add_f32_e32 v1, v1, v88
	v_add_f32_e32 v1, v1, v89
	s_waitcnt lgkmcnt(0)
	v_add_f32_e32 v5, v0, v2
	v_mul_f32_e32 v0, 0x4b800000, v38
	v_mov_b32_e32 v200, v1
	v_mov_b32_e32 v201, v1
	s_nop 1
	v_permlane32_swap_b32 v200, v201
	v_cndmask_b32_e64 v3, v201, v200, s[20:21]
	v_cndmask_b32_e32 v0, v38, v0, vcc
	v_rsq_f32_e32 v0, v0
	v_mov_b32_e32 v200, v5
	v_mov_b32_e32 v201, v5
	s_nop 1
	v_permlane16_swap_b32 v200, v201
	v_cndmask_b32_e64 v96, v201, v200, s[22:23]
	s_waitcnt lgkmcnt(1)
	v_add_f32_e32 v95, v1, v3
	v_mul_f32_e32 v1, 0x45800000, v0
	v_cndmask_b32_e32 v94, v0, v1, vcc
	v_pk_mul_f32 v[2:3], v[30:31], v[94:95] op_sel_hi:[1,0]
	v_pk_mul_f32 v[0:1], v[28:29], v[94:95] op_sel_hi:[1,0]
	v_pk_mul_f32 v[30:31], v[34:35], v[94:95] op_sel_hi:[1,0]
	v_pk_mul_f32 v[28:29], v[32:33], v[94:95] op_sel_hi:[1,0]
	v_mov_b32_e32 v200, v95
	v_mov_b32_e32 v201, v95
	s_nop 1
	v_permlane16_swap_b32 v200, v201
	v_cndmask_b32_e64 v97, v201, v200, s[22:23]
	v_pk_mul_f32 v[22:23], v[22:23], v[94:95] op_sel_hi:[1,0]
	v_pk_mul_f32 v[18:19], v[18:19], v[94:95] op_sel_hi:[1,0]
	v_pk_mul_f32 v[26:27], v[26:27], v[94:95] op_sel_hi:[1,0]
	v_pk_fma_f32 v[28:29], v[40:41], v[28:29], v[54:55]
	v_pk_fma_f32 v[0:1], v[44:45], v[0:1], v[58:59]
	v_pk_fma_f32 v[2:3], v[46:47], v[2:3], v[60:61]
	v_pk_fma_f32 v[30:31], v[42:43], v[30:31], v[56:57]
	global_store_dwordx4 v[36:37], v[0:3], off
	global_store_dwordx4 v[36:37], v[28:31], off offset:16
	v_mov_b32_e32 v32, v140
	v_mov_b32_e32 v33, v141
	v_mov_b32_e32 v34, v142
	v_mov_b32_e32 v35, v143
	v_mov_b32_e32 v38, v136
	v_mov_b32_e32 v39, v137
	v_mov_b32_e32 v40, v138
	v_mov_b32_e32 v41, v139
	v_mov_b32_e32 v42, v124
	v_mov_b32_e32 v43, v125
	v_mov_b32_e32 v44, v126
	v_mov_b32_e32 v45, v127
	v_mov_b32_e32 v54, v120
	v_mov_b32_e32 v55, v121
	v_mov_b32_e32 v56, v122
	v_mov_b32_e32 v57, v123
	s_waitcnt lgkmcnt(1)
	v_add_f32_e32 v0, v5, v96
	s_waitcnt lgkmcnt(0)
	v_add_f32_e32 v1, v95, v97
	s_nop 1
	v_mov_b32_dpp v2, v0 row_ror:8 row_mask:0xf bank_mask:0xf
	s_nop 1
	v_mov_b32_dpp v3, v1 row_ror:8 row_mask:0xf bank_mask:0xf
	v_pk_mul_f32 v[94:95], v[20:21], v[94:95] op_sel_hi:[1,0]
	s_waitcnt lgkmcnt(1)
	v_add_f32_e32 v0, v0, v2
	s_waitcnt lgkmcnt(0)
	v_add_f32_e32 v1, v1, v3
	s_nop 1
	v_mov_b32_dpp v2, v0 row_shl:4 row_mask:0xf bank_mask:0x5
	v_mov_b32_dpp v2, v0 row_shr:4 row_mask:0xf bank_mask:0xa
	s_nop 1
	v_mov_b32_dpp v3, v1 row_shl:4 row_mask:0xf bank_mask:0x5
	v_mov_b32_dpp v3, v1 row_shr:4 row_mask:0xf bank_mask:0xa
	s_waitcnt lgkmcnt(1)
	v_add_f32_e32 v0, v0, v2
	s_waitcnt lgkmcnt(0)
	v_add_f32_e32 v1, v1, v3
	s_nop 1
	v_mov_b32_dpp v2, v0 quad_perm:[2,3,0,1] row_mask:0xf bank_mask:0xf
	s_nop 1
	v_mov_b32_dpp v3, v1 quad_perm:[2,3,0,1] row_mask:0xf bank_mask:0xf
	s_waitcnt lgkmcnt(1)
	v_add_f32_e32 v0, v0, v2
	s_waitcnt lgkmcnt(0)
	v_add_f32_e32 v1, v1, v3
	s_nop 1
	v_mov_b32_dpp v2, v0 quad_perm:[1,0,3,2] row_mask:0xf bank_mask:0xf
	s_nop 1
	v_mov_b32_dpp v3, v1 quad_perm:[1,0,3,2] row_mask:0xf bank_mask:0xf
	s_waitcnt lgkmcnt(1)
	v_add_f32_e32 v0, v0, v2
	s_waitcnt lgkmcnt(0)
	v_add_f32_e32 v1, v1, v3
	v_mul_f32_e32 v0, 0x3a800000, v0
	v_mul_f32_e32 v30, 0x3a800000, v1
	v_pk_add_f32 v[46:47], v[64:65], v[0:1] op_sel_hi:[1,0] neg_lo:[0,1] neg_hi:[0,1]
	v_pk_add_f32 v[64:65], v[72:73], v[0:1] op_sel_hi:[1,0] neg_lo:[0,1] neg_hi:[0,1]
	v_pk_add_f32 v[72:73], v[84:85], v[30:31] op_sel_hi:[1,0] neg_lo:[0,1] neg_hi:[0,1]
	v_pk_add_f32 v[58:59], v[66:67], v[0:1] op_sel_hi:[1,0] neg_lo:[0,1] neg_hi:[0,1]
	v_pk_add_f32 v[60:61], v[82:83], v[0:1] op_sel_hi:[1,0] neg_lo:[0,1] neg_hi:[0,1]
	v_pk_add_f32 v[62:63], v[62:63], v[0:1] op_sel_hi:[1,0] neg_lo:[0,1] neg_hi:[0,1]
	v_pk_add_f32 v[66:67], v[74:75], v[0:1] op_sel_hi:[1,0] neg_lo:[0,1] neg_hi:[0,1]
	v_pk_add_f32 v[68:69], v[68:69], v[0:1] op_sel_hi:[1,0] neg_lo:[0,1] neg_hi:[0,1]
	v_pk_add_f32 v[70:71], v[70:71], v[0:1] op_sel_hi:[1,0] neg_lo:[0,1] neg_hi:[0,1]
	v_pk_add_f32 v[74:75], v[78:79], v[30:31] op_sel_hi:[1,0] neg_lo:[0,1] neg_hi:[0,1]
	v_pk_add_f32 v[76:77], v[76:77], v[30:31] op_sel_hi:[1,0] neg_lo:[0,1] neg_hi:[0,1]
	v_pk_add_f32 v[78:79], v[80:81], v[30:31] op_sel_hi:[1,0] neg_lo:[0,1] neg_hi:[0,1]
	v_pk_add_f32 v[0:1], v[90:91], v[30:31] op_sel_hi:[1,0] neg_lo:[0,1] neg_hi:[0,1]
	v_pk_add_f32 v[28:29], v[92:93], v[30:31] op_sel_hi:[1,0] neg_lo:[0,1] neg_hi:[0,1]
	v_pk_add_f32 v[2:3], v[86:87], v[30:31] op_sel_hi:[1,0] neg_lo:[0,1] neg_hi:[0,1]
	v_pk_add_f32 v[30:31], v[88:89], v[30:31] op_sel_hi:[1,0] neg_lo:[0,1] neg_hi:[0,1]
	v_mov_b32_e32 v86, v73
	v_mov_b32_e32 v87, v47
	v_pk_mul_f32 v[82:83], v[70:71], v[70:71]
	v_mov_b32_e32 v84, v72
	v_mov_b32_e32 v85, v46
	v_mov_b32_e32 v88, v74
	v_mov_b32_e32 v89, v58
	v_mov_b32_e32 v92, v75
	v_mov_b32_e32 v93, v59
	v_mov_b32_e32 v96, v76
	v_mov_b32_e32 v97, v60
	v_mov_b32_e32 v98, v77
	v_mov_b32_e32 v99, v61
	v_mov_b32_e32 v100, v78
	v_mov_b32_e32 v101, v62
	v_mov_b32_e32 v102, v79
	v_mov_b32_e32 v103, v63
	v_mov_b32_e32 v104, v0
	v_mov_b32_e32 v105, v64
	v_mov_b32_e32 v106, v1
	v_mov_b32_e32 v107, v65
	v_mov_b32_e32 v108, v28
	v_mov_b32_e32 v109, v66
	v_pk_mul_f32 v[80:81], v[68:69], v[68:69]
	v_pk_mul_f32 v[90:91], v[2:3], v[2:3]
	v_mov_b32_e32 v110, v29
	v_mov_b32_e32 v111, v67
	v_pk_fma_f32 v[32:33], v[32:33], v[94:95], v[42:43]
	v_pk_fma_f32 v[18:19], v[38:39], v[18:19], v[54:55]
	v_pk_fma_f32 v[20:21], v[40:41], v[22:23], v[56:57]
	v_pk_fma_f32 v[34:35], v[34:35], v[26:27], v[44:45]
	global_store_dwordx4 v[36:37], v[18:21], off offset:2048
	global_store_dwordx4 v[36:37], v[32:35], off offset:2064
	s_nop 0
	v_mov_b32_e32 v18, v132
	v_mov_b32_e32 v19, v133
	v_mov_b32_e32 v20, v134
	v_mov_b32_e32 v21, v135
	s_nop 0
	v_mov_b32_e32 v32, v128
	v_mov_b32_e32 v33, v129
	v_mov_b32_e32 v34, v130
	v_mov_b32_e32 v35, v131
	v_mov_b32_e32 v36, v116
	v_mov_b32_e32 v37, v117
	v_mov_b32_e32 v38, v118
	v_mov_b32_e32 v39, v119
	v_mov_b32_e32 v40, v112
	v_mov_b32_e32 v41, v113
	v_mov_b32_e32 v42, v114
	v_mov_b32_e32 v43, v115
	v_pk_mul_f32 v[22:23], v[30:31], v[30:31]
	v_pk_mul_f32 v[26:27], v[86:87], v[86:87]
	v_mov_b32_e32 v54, v22
	v_mov_b32_e32 v55, v82
	v_mov_b32_e32 v82, v23
	v_pk_fma_f32 v[22:23], v[84:85], v[84:85], v[26:27]
	v_mov_b32_e32 v44, v90
	v_pk_fma_f32 v[22:23], v[88:89], v[88:89], v[22:23]
	v_mov_b32_e32 v45, v80
	v_pk_fma_f32 v[22:23], v[92:93], v[92:93], v[22:23]
	v_mov_b32_e32 v80, v91
	v_pk_fma_f32 v[22:23], v[96:97], v[96:97], v[22:23]
	s_nop 0
	v_pk_fma_f32 v[22:23], v[98:99], v[98:99], v[22:23]
	s_nop 0
	v_pk_fma_f32 v[22:23], v[100:101], v[100:101], v[22:23]
	s_nop 0
	v_pk_fma_f32 v[22:23], v[102:103], v[102:103], v[22:23]
	s_nop 0
	v_pk_fma_f32 v[22:23], v[104:105], v[104:105], v[22:23]
	s_nop 0
	v_pk_fma_f32 v[22:23], v[106:107], v[106:107], v[22:23]
	s_nop 0
	v_pk_fma_f32 v[22:23], v[108:109], v[108:109], v[22:23]
	s_nop 0
	v_pk_fma_f32 v[22:23], v[110:111], v[110:111], v[22:23]
	s_nop 0
	v_pk_add_f32 v[22:23], v[44:45], v[22:23]
	s_nop 0
	v_pk_add_f32 v[22:23], v[80:81], v[22:23]
	s_nop 0
	v_pk_add_f32 v[22:23], v[54:55], v[22:23]
	s_nop 0
	v_pk_add_f32 v[22:23], v[82:83], v[22:23]
	v_mov_b32_e32 v200, v23
	v_mov_b32_e32 v201, v23
	s_nop 1
	v_permlane32_swap_b32 v200, v201
	v_cndmask_b32_e64 v27, v201, v200, s[20:21]
	v_mov_b32_e32 v200, v22
	v_mov_b32_e32 v201, v22
	s_nop 1
	v_permlane32_swap_b32 v200, v201
	v_cndmask_b32_e64 v26, v201, v200, s[20:21]
	s_waitcnt lgkmcnt(0)
	v_pk_add_f32 v[22:23], v[22:23], v[26:27]
	v_mov_b32_e32 v200, v23
	v_mov_b32_e32 v201, v23
	s_nop 1
	v_permlane16_swap_b32 v200, v201
	v_cndmask_b32_e64 v27, v201, v200, s[22:23]
	v_mov_b32_e32 v200, v22
	v_mov_b32_e32 v201, v22
	s_nop 1
	v_permlane16_swap_b32 v200, v201
	v_cndmask_b32_e64 v26, v201, v200, s[22:23]
	s_waitcnt lgkmcnt(0)
	v_pk_add_f32 v[22:23], v[22:23], v[26:27]
	s_nop 1
	v_mov_b32_dpp v27, v23 row_ror:8 row_mask:0xf bank_mask:0xf
	s_nop 1
	v_mov_b32_dpp v26, v22 row_ror:8 row_mask:0xf bank_mask:0xf
	s_waitcnt lgkmcnt(0)
	v_pk_add_f32 v[22:23], v[22:23], v[26:27]
	s_nop 1
	v_mov_b32_dpp v27, v23 row_shl:4 row_mask:0xf bank_mask:0x5
	v_mov_b32_dpp v27, v23 row_shr:4 row_mask:0xf bank_mask:0xa
	s_nop 1
	v_mov_b32_dpp v26, v22 row_shl:4 row_mask:0xf bank_mask:0x5
	v_mov_b32_dpp v26, v22 row_shr:4 row_mask:0xf bank_mask:0xa
	s_waitcnt lgkmcnt(0)
	v_pk_add_f32 v[22:23], v[22:23], v[26:27]
	s_nop 1
	v_mov_b32_dpp v27, v23 quad_perm:[2,3,0,1] row_mask:0xf bank_mask:0xf
	s_nop 1
	v_mov_b32_dpp v26, v22 quad_perm:[2,3,0,1] row_mask:0xf bank_mask:0xf
	s_waitcnt lgkmcnt(0)
	v_pk_add_f32 v[22:23], v[22:23], v[26:27]
	s_nop 1
	v_mov_b32_dpp v27, v23 quad_perm:[1,0,3,2] row_mask:0xf bank_mask:0xf
	s_nop 1
	v_mov_b32_dpp v26, v22 quad_perm:[1,0,3,2] row_mask:0xf bank_mask:0xf
	s_waitcnt lgkmcnt(0)
	v_pk_add_f32 v[22:23], v[22:23], v[26:27]
	s_nop 0
	v_pk_fma_f32 v[26:27], v[22:23], s[2:3], v[14:15] op_sel_hi:[1,0,0]
	v_lshlrev_b64 v[22:23], 12, v[24:25]
	v_mul_f32_e32 v5, 0x4b800000, v27
	v_cmp_gt_f32_e32 vcc, s4, v27
	v_lshl_add_u64 v[44:45], v[12:13], 0, v[22:23]
	s_nop 0
	v_cndmask_b32_e32 v5, v27, v5, vcc
	v_rsq_f32_e32 v5, v5
	s_nop 0
	v_mul_f32_e32 v22, 0x45800000, v5
	v_cndmask_b32_e32 v54, v5, v22, vcc
	v_pk_mul_f32 v[24:25], v[58:59], v[54:55] op_sel_hi:[1,0]
	v_pk_mul_f32 v[22:23], v[46:47], v[54:55] op_sel_hi:[1,0]
	v_pk_mul_f32 v[46:47], v[62:63], v[54:55] op_sel_hi:[1,0]
	v_pk_mul_f32 v[56:57], v[60:61], v[54:55] op_sel_hi:[1,0]
	v_pk_fma_f32 v[22:23], v[32:33], v[22:23], v[40:41]
	v_pk_fma_f32 v[24:25], v[34:35], v[24:25], v[42:43]
	v_pk_fma_f32 v[18:19], v[18:19], v[56:57], v[36:37]
	v_pk_fma_f32 v[20:21], v[20:21], v[46:47], v[38:39]
	global_store_dwordx4 v[44:45], v[22:25], off
	global_store_dwordx4 v[44:45], v[18:21], off offset:16
	s_nop 1
	v_mov_b32_e32 v18, v120
	v_mov_b32_e32 v19, v121
	v_mov_b32_e32 v20, v122
	v_mov_b32_e32 v21, v123
	s_nop 0
	v_mov_b32_e32 v22, v136
	v_mov_b32_e32 v23, v137
	v_mov_b32_e32 v24, v138
	v_mov_b32_e32 v25, v139
	v_mov_b32_e32 v32, v140
	v_mov_b32_e32 v33, v141
	v_mov_b32_e32 v34, v142
	v_mov_b32_e32 v35, v143
	v_mov_b32_e32 v36, v124
	v_mov_b32_e32 v37, v125
	v_mov_b32_e32 v38, v126
	v_mov_b32_e32 v39, v127
	v_pk_mul_f32 v[40:41], v[66:67], v[54:55] op_sel_hi:[1,0]
	v_pk_mul_f32 v[42:43], v[64:65], v[54:55] op_sel_hi:[1,0]
	v_pk_mul_f32 v[46:47], v[70:71], v[54:55] op_sel_hi:[1,0]
	v_pk_mul_f32 v[54:55], v[68:69], v[54:55] op_sel_hi:[1,0]
	v_mul_f32_e32 v5, 0x4b800000, v26
	v_cmp_gt_f32_e32 vcc, s4, v26
	v_pk_fma_f32 v[18:19], v[22:23], v[42:43], v[18:19]
	v_pk_fma_f32 v[20:21], v[24:25], v[40:41], v[20:21]
	v_pk_fma_f32 v[22:23], v[32:33], v[54:55], v[36:37]
	v_pk_fma_f32 v[24:25], v[34:35], v[46:47], v[38:39]
	global_store_dwordx4 v[44:45], v[18:21], off offset:2048
	global_store_dwordx4 v[44:45], v[22:25], off offset:2064
	s_nop 0
	v_mov_b32_e32 v18, v112
	v_mov_b32_e32 v19, v113
	v_mov_b32_e32 v20, v114
	v_mov_b32_e32 v21, v115
	s_nop 0
	v_mov_b32_e32 v22, v128
	v_mov_b32_e32 v23, v129
	v_mov_b32_e32 v24, v130
	v_mov_b32_e32 v25, v131
	v_mov_b32_e32 v32, v132
	v_mov_b32_e32 v33, v133
	v_mov_b32_e32 v34, v134
	v_mov_b32_e32 v35, v135
	v_mov_b32_e32 v36, v116
	v_mov_b32_e32 v37, v117
	v_mov_b32_e32 v38, v118
	v_mov_b32_e32 v39, v119
	v_cndmask_b32_e32 v5, v26, v5, vcc
	v_rsq_f32_e32 v5, v5
	v_lshl_add_u64 v[40:41], v[12:13], 0, v[16:17]
	v_mul_f32_e32 v16, 0x45800000, v5
	v_cndmask_b32_e32 v42, v5, v16, vcc
	v_pk_mul_f32 v[26:27], v[74:75], v[42:43] op_sel_hi:[1,0]
	v_pk_mul_f32 v[16:17], v[72:73], v[42:43] op_sel_hi:[1,0]
	v_pk_mul_f32 v[44:45], v[78:79], v[42:43] op_sel_hi:[1,0]
	v_pk_mul_f32 v[46:47], v[76:77], v[42:43] op_sel_hi:[1,0]
	v_cmp_lt_i32_e32 vcc, s5, v4
	v_pk_mul_f32 v[28:29], v[28:29], v[42:43] op_sel_hi:[1,0]
	v_pk_mul_f32 v[0:1], v[0:1], v[42:43] op_sel_hi:[1,0]
	s_or_b64 s[0:1], vcc, s[0:1]
	v_pk_mul_f32 v[30:31], v[30:31], v[42:43] op_sel_hi:[1,0]
	v_pk_fma_f32 v[16:17], v[22:23], v[16:17], v[18:19]
	v_pk_fma_f32 v[18:19], v[24:25], v[26:27], v[20:21]
	v_pk_fma_f32 v[20:21], v[32:33], v[46:47], v[36:37]
	v_pk_fma_f32 v[22:23], v[34:35], v[44:45], v[38:39]
	global_store_dwordx4 v[40:41], v[16:19], off
	global_store_dwordx4 v[40:41], v[20:23], off offset:16
	s_nop 0
	v_mov_b32_e32 v16, v120
	v_mov_b32_e32 v17, v121
	v_mov_b32_e32 v18, v122
	v_mov_b32_e32 v19, v123
	s_nop 0
	v_mov_b32_e32 v20, v136
	v_mov_b32_e32 v21, v137
	v_mov_b32_e32 v22, v138
	v_mov_b32_e32 v23, v139
	v_mov_b32_e32 v24, v140
	v_mov_b32_e32 v25, v141
	v_mov_b32_e32 v26, v142
	v_mov_b32_e32 v27, v143
	v_mov_b32_e32 v32, v124
	v_mov_b32_e32 v33, v125
	v_mov_b32_e32 v34, v126
	v_mov_b32_e32 v35, v127
	v_pk_mul_f32 v[36:37], v[2:3], v[42:43] op_sel_hi:[1,0]
	v_pk_fma_f32 v[0:1], v[20:21], v[0:1], v[16:17]
	v_pk_fma_f32 v[2:3], v[22:23], v[28:29], v[18:19]
	v_pk_fma_f32 v[16:17], v[24:25], v[36:37], v[32:33]
	v_pk_fma_f32 v[18:19], v[26:27], v[30:31], v[34:35]
	global_store_dwordx4 v[40:41], v[0:3], off offset:2048
	global_store_dwordx4 v[40:41], v[16:19], off offset:2064
	s_andn2_b64 exec, exec, s[0:1]
	s_cbranch_execnz .LBB0_1619
